# K-loop: SGPR temp renamed so tile bases stay live; 18 address pairs + 37 single loads now scalar-base (73 of 80 LDS-DMA loads without 64-bit VALU adds); setprio flips deleted; previous edits
# speedup vs baseline: 1.0019x; 1.0019x over previous
;     __device__ __forceinline__ void prefetch(const Unit& u, int wr, int wc, int lane) const { lnfold_prefetch(vl, stats, gW, bW, u, wr, wc, lane); }
;     __device__ __forceinline__ void prefetch(const Unit& u, int wr, int wc, int lane) const { lnfold_prefetch(vl, stats, gW, bW, u, wr, wc, lane); }
; #define PG8_STAGE(bufoff, gbase, voff) do { _Pragma("unroll") for (int _i = 0; _i < 2; ++_i) \
;         __builtin_amdgcn_global_load_lds((const unsigned*)((const char*)(gbase) + (voff)[_i]), (LAS unsigned*)(lds + (bufoff) + ldsw + _i * 8192), 16, 0, 0); } while (0)
; #define PG8_LDA(dst, b, h) do { _Pragma("unroll") for (int m = 0; m < 4; ++m) _Pragma("unroll") for (int k = 0; k < 2; ++k) dst[m][k] = *(const LAS f16x8*)(lds + PG8_SA(b, h) + aoff + m * 2048 + k * 1024); } while (0)
; #define PG8_LDB(dst, b, h) do { _Pragma("unroll") for (int n = 0; n < 2; ++n) _Pragma("unroll") for (int k = 0; k < 2; ++k) dst[n][k] = *(const LAS f16x8*)(lds + PG8_SB(b, h) + boff + n * 2048 + k * 1024); } while (0)
; template <class Epi>
; __device__ __forceinline__ void gemm_phase(LAS unsigned char* lds, const Gemm g0, const StaticOrder& S, const Epi& E) {
;     ...
;         const char* nA = has_next ? (const char*)g.A + (size_t)nxt.pm * tstep : cA; const char* nB = has_next ? (const char*)g.Bt + (size_t)nxt.pn * tstep : cB;
;         for (int t = 0; t < nt; t += 2) {
;             const bool last = (t == nt - 2);
;             if (Epi::PREF && last) E.prefetch(cur, wr, wc, lane);
;             const char* a1 = cA + (size_t)(t + 1) * kstep;
;             const char* a2 = last ? nA : cA + (size_t)(t + 2) * kstep; const char* b2 = last ? nB : cB + (size_t)(t + 2) * kstep;
;             const char* a3 = a2 + kstep; const char* b3 = b2 + kstep;
;             PG8_LDB(B0, 0, 0); PG8_SCHED; PG8_LDA(At, 0, 0); PG8_STAGE(PG8_SA(1, 1), a1 + hstep, voffA);
;             PG8_WAIT_L(8); PG8_BAR; PG8_WAIT_L(0); PG8_MMA(0, 0, At, B0); PG8_BAR; PG8_SCHED;
;             PG8_LDB(B1, 0, 1); PG8_STAGE(PG8_SB(0, 0), b2, voffB);
;             PG8_BAR; PG8_WAIT_L(0); PG8_MMA(0, 1, At, B1); PG8_BAR;
;             PG8_LDA(At, 0, 1); PG8_STAGE(PG8_SA(0, 0), a2, voffA);
;             PG8_BAR; PG8_WAIT_L(0); PG8_MMA(1, 0, At, B0); PG8_BAR; PG8_SCHED;
;             PG8_STAGE(PG8_SB(0, 1), b2 + hstep, voffB);
;             PG8_WAIT_V(6); PG8_BAR; PG8_MMA(1, 1, At, B1); PG8_BAR;
.LBB0_198:
	s_add_u32 s52, s0, 0xfff80080
	s_addc_u32 s53, s1, -1
	s_and_b64 s[22:23], s[50:51], exec
	s_cselect_b32 s53, s75, s53
	s_cselect_b32 s52, s80, s52
	s_add_i32 s84, 0, 0x10000
	v_add_u32_e32 v148, s84, v214
	ds_read_b128 v[136:139], v148
	ds_read_b128 v[140:143], v148 offset:1024
	ds_read_b128 v[144:147], v148 offset:2048
	ds_read_b128 v[148:151], v148 offset:3072
	s_and_b64 s[22:23], s[50:51], exec
	s_cselect_b32 s51, s81, s25
	s_cselect_b32 s50, s82, s24
	s_add_i32 m0, s28, 0xc000
	ds_read_b128 v[152:155], v222
	ds_read_b128 v[156:159], v222 offset:1024
	ds_read_b128 v[186:189], v222 offset:2048
	ds_read_b128 v[190:193], v222 offset:3072
	ds_read_b128 v[194:197], v222 offset:4096
	ds_read_b128 v[198:201], v222 offset:5120
	ds_read_b128 v[202:205], v222 offset:6144
	ds_read_b128 v[206:209], v222 offset:7168
	global_load_lds_dwordx4 v184, s[0:1]
	s_add_i32 m0, s28, 0xe000
	s_nop 0
	global_load_lds_dwordx4 v182, s[0:1]
	s_waitcnt lgkmcnt(8)
	s_barrier
	s_waitcnt lgkmcnt(0)
	s_waitcnt lgkmcnt(0)
	v_mfma_f32_16x16x32_f16 v[126:129], v[136:139], v[152:155], v[126:129]
	v_mfma_f32_16x16x32_f16 v[122:125], v[144:147], v[152:155], v[122:125]
	v_mfma_f32_16x16x32_f16 v[118:121], v[136:139], v[186:189], v[118:121]
	v_mfma_f32_16x16x32_f16 v[110:113], v[144:147], v[186:189], v[110:113]
	v_mfma_f32_16x16x32_f16 v[102:105], v[136:139], v[194:197], v[102:105]
	v_mfma_f32_16x16x32_f16 v[98:101], v[144:147], v[194:197], v[98:101]
	v_mfma_f32_16x16x32_f16 v[86:89], v[136:139], v[202:205], v[86:89]
	v_mfma_f32_16x16x32_f16 v[82:85], v[144:147], v[202:205], v[82:85]
	v_mfma_f32_16x16x32_f16 v[126:129], v[140:143], v[156:159], v[126:129]
	v_mfma_f32_16x16x32_f16 v[122:125], v[148:151], v[156:159], v[122:125]
	v_mfma_f32_16x16x32_f16 v[118:121], v[140:143], v[190:193], v[118:121]
	v_mfma_f32_16x16x32_f16 v[110:113], v[148:151], v[190:193], v[110:113]
	v_mfma_f32_16x16x32_f16 v[102:105], v[140:143], v[198:201], v[102:105]
	v_mfma_f32_16x16x32_f16 v[98:101], v[148:151], v[198:201], v[98:101]
	v_mfma_f32_16x16x32_f16 v[86:89], v[140:143], v[206:209], v[86:89]
	v_mfma_f32_16x16x32_f16 v[82:85], v[148:151], v[206:209], v[82:85]
	s_barrier
	s_add_i32 s85, 0, 0x14000
	v_add_u32_e32 v160, s85, v214
	s_add_i32 s22, s84, s19
	ds_read_b128 v[210:213], v160
	ds_read_b128 v[234:237], v160 offset:1024
	ds_read_b128 v[238:241], v160 offset:2048
	ds_read_b128 v[242:245], v160 offset:3072
	v_add_u32_e32 v160, 0x80, v178
	s_mov_b32 m0, s22
	v_add_u32_e32 v162, 0x80, v174
	global_load_lds_dwordx4 v178, s[50:51]
	s_add_i32 m0, s22, 0x2000
	s_nop 0
	global_load_lds_dwordx4 v174, s[50:51]
	s_barrier
	s_waitcnt lgkmcnt(0)
	s_waitcnt lgkmcnt(0)
	v_mfma_f32_16x16x32_f16 v[114:117], v[210:213], v[152:155], v[114:117]
	v_mfma_f32_16x16x32_f16 v[106:109], v[238:241], v[152:155], v[106:109]
	v_mfma_f32_16x16x32_f16 v[94:97], v[210:213], v[186:189], v[94:97]
	v_mfma_f32_16x16x32_f16 v[90:93], v[238:241], v[186:189], v[90:93]
	v_mfma_f32_16x16x32_f16 v[78:81], v[210:213], v[194:197], v[78:81]
	v_mfma_f32_16x16x32_f16 v[74:77], v[238:241], v[194:197], v[74:77]
	v_mfma_f32_16x16x32_f16 v[70:73], v[210:213], v[202:205], v[70:73]
	v_mfma_f32_16x16x32_f16 v[66:69], v[238:241], v[202:205], v[66:69]
	v_mfma_f32_16x16x32_f16 v[114:117], v[234:237], v[156:159], v[114:117]
	v_mfma_f32_16x16x32_f16 v[106:109], v[242:245], v[156:159], v[106:109]
	v_mfma_f32_16x16x32_f16 v[94:97], v[234:237], v[190:193], v[94:97]
	v_mfma_f32_16x16x32_f16 v[90:93], v[242:245], v[190:193], v[90:93]
	v_mfma_f32_16x16x32_f16 v[78:81], v[234:237], v[198:201], v[78:81]
	v_mfma_f32_16x16x32_f16 v[74:77], v[242:245], v[198:201], v[74:77]
	v_mfma_f32_16x16x32_f16 v[70:73], v[234:237], v[206:209], v[70:73]
	v_mfma_f32_16x16x32_f16 v[66:69], v[242:245], v[206:209], v[66:69]
	s_mov_b32 m0, s28
	v_add_u32_e32 v164, 0x80, v180
	s_barrier
	ds_read_b128 v[152:155], v222 offset:16384
	ds_read_b128 v[156:159], v222 offset:17408
	ds_read_b128 v[186:189], v222 offset:18432
	ds_read_b128 v[190:193], v222 offset:19456
	ds_read_b128 v[194:197], v222 offset:20480
	ds_read_b128 v[198:201], v222 offset:21504
	ds_read_b128 v[202:205], v222 offset:22528
	ds_read_b128 v[206:209], v222 offset:23552
	global_load_lds_dwordx4 v180, s[52:53]
	v_add_u32_e32 v170, 0x80, v176
	s_mov_b32 m0, s29
	s_nop 0
	global_load_lds_dwordx4 v176, s[52:53]
	s_barrier
	s_waitcnt lgkmcnt(0)
	s_waitcnt lgkmcnt(0)
	v_mfma_f32_16x16x32_f16 v[62:65], v[136:139], v[152:155], v[62:65]
	v_mfma_f32_16x16x32_f16 v[58:61], v[144:147], v[152:155], v[58:61]
	v_mfma_f32_16x16x32_f16 v[54:57], v[136:139], v[186:189], v[54:57]
	v_mfma_f32_16x16x32_f16 v[50:53], v[144:147], v[186:189], v[50:53]
	v_mfma_f32_16x16x32_f16 v[38:41], v[136:139], v[194:197], v[38:41]
	v_mfma_f32_16x16x32_f16 v[30:33], v[144:147], v[194:197], v[30:33]
	v_mfma_f32_16x16x32_f16 v[22:25], v[136:139], v[202:205], v[22:25]
	v_mfma_f32_16x16x32_f16 v[18:21], v[144:147], v[202:205], v[18:21]
	v_mfma_f32_16x16x32_f16 v[62:65], v[140:143], v[156:159], v[62:65]
	v_mfma_f32_16x16x32_f16 v[58:61], v[148:151], v[156:159], v[58:61]
	v_mfma_f32_16x16x32_f16 v[54:57], v[140:143], v[190:193], v[54:57]
	v_mfma_f32_16x16x32_f16 v[50:53], v[148:151], v[190:193], v[50:53]
	v_mfma_f32_16x16x32_f16 v[38:41], v[140:143], v[198:201], v[38:41]
	v_mfma_f32_16x16x32_f16 v[30:33], v[148:151], v[198:201], v[30:33]
	v_mfma_f32_16x16x32_f16 v[22:25], v[140:143], v[206:209], v[22:25]
	v_mfma_f32_16x16x32_f16 v[18:21], v[148:151], v[206:209], v[18:21]
	s_barrier
	s_add_u32 s22, s50, 0x80000
	s_addc_u32 s23, s51, 0
	s_add_i32 s84, s85, s19
	s_mov_b32 m0, s84
	s_nop 0
	global_load_lds_dwordx4 v178, s[22:23]
	s_add_i32 m0, s84, 0x2000
	s_nop 0
	global_load_lds_dwordx4 v174, s[22:23]
	s_waitcnt vmcnt(6)
	s_barrier
; #define PG8_STAGE(bufoff, gbase, voff) do { _Pragma("unroll") for (int _i = 0; _i < 2; ++_i) \
;         __builtin_amdgcn_global_load_lds((const unsigned*)((const char*)(gbase) + (voff)[_i]), (LAS unsigned*)(lds + (bufoff) + ldsw + _i * 8192), 16, 0, 0); } while (0)
; #define PG8_LDA(dst, b, h) do { _Pragma("unroll") for (int m = 0; m < 4; ++m) _Pragma("unroll") for (int k = 0; k < 2; ++k) dst[m][k] = *(const LAS f16x8*)(lds + PG8_SA(b, h) + aoff + m * 2048 + k * 1024); } while (0)
; #define PG8_LDB(dst, b, h) do { _Pragma("unroll") for (int n = 0; n < 2; ++n) _Pragma("unroll") for (int k = 0; k < 2; ++k) dst[n][k] = *(const LAS f16x8*)(lds + PG8_SB(b, h) + boff + n * 2048 + k * 1024); } while (0)
; #define PG8_MMA(ai, bj, At, Bt) do { __builtin_amdgcn_s_setprio(1); _Pragma("unroll") for (int m = 0; m < 4; ++m) _Pragma("unroll") for (int n = 0; n < 2; ++n) _Pragma("unroll") for (int k = 0; k < 2; ++k) \
;         acc[ai][bj][m][n] = __builtin_amdgcn_mfma_f32_16x16x32_f16(Bt[n][k], At[m][k], acc[ai][bj][m][n], 0, 0, 0); __builtin_amdgcn_s_setprio(0); } while (0)
; #define PG8_WAIT_V(n) asm volatile("s_waitcnt vmcnt(" #n ")" ::: "memory")
; #define PG8_WAIT_L(n) asm volatile("s_waitcnt lgkmcnt(" #n ")" ::: "memory")
; #define PG8_BAR __builtin_amdgcn_s_barrier()
; #define PG8_SCHED __builtin_amdgcn_sched_barrier(0)
; template <class Epi>
; __device__ __forceinline__ void gemm_phase(LAS unsigned char* lds, const Gemm g0, const StaticOrder& S, const Epi& E) {
;     ...
;             PG8_WAIT_V(6); PG8_BAR; PG8_MMA(1, 1, At, B1); PG8_BAR;
;             PG8_LDB(B0, 1, 0); PG8_SCHED; PG8_LDA(At, 1, 0); PG8_STAGE(PG8_SA(0, 1), a2 + hstep, voffA);
;             PG8_WAIT_L(8); PG8_BAR; PG8_WAIT_L(0); PG8_MMA(0, 0, At, B0); PG8_BAR; PG8_SCHED;
;             PG8_LDB(B1, 1, 1); PG8_STAGE(PG8_SB(1, 0), b3, voffB);
	v_mfma_f32_16x16x32_f16 v[46:49], v[210:213], v[152:155], v[46:49]
	v_mfma_f32_16x16x32_f16 v[42:45], v[238:241], v[152:155], v[42:45]
	v_mfma_f32_16x16x32_f16 v[34:37], v[210:213], v[186:189], v[34:37]
	v_mfma_f32_16x16x32_f16 v[26:29], v[238:241], v[186:189], v[26:29]
	v_mfma_f32_16x16x32_f16 v[14:17], v[210:213], v[194:197], v[14:17]
	v_mfma_f32_16x16x32_f16 v[10:13], v[238:241], v[194:197], v[10:13]
	v_mfma_f32_16x16x32_f16 v[6:9], v[210:213], v[202:205], v[6:9]
	v_mfma_f32_16x16x32_f16 v[2:5], v[238:241], v[202:205], v[2:5]
	v_mfma_f32_16x16x32_f16 v[46:49], v[234:237], v[156:159], v[46:49]
	v_mfma_f32_16x16x32_f16 v[42:45], v[242:245], v[156:159], v[42:45]
	v_mfma_f32_16x16x32_f16 v[34:37], v[234:237], v[190:193], v[34:37]
	v_mfma_f32_16x16x32_f16 v[26:29], v[242:245], v[190:193], v[26:29]
	v_mfma_f32_16x16x32_f16 v[14:17], v[234:237], v[198:201], v[14:17]
	v_mfma_f32_16x16x32_f16 v[10:13], v[242:245], v[198:201], v[10:13]
	v_mfma_f32_16x16x32_f16 v[6:9], v[234:237], v[206:209], v[6:9]
	v_mfma_f32_16x16x32_f16 v[2:5], v[242:245], v[206:209], v[2:5]
	s_add_i32 s84, 0, 0x18000
	v_add_u32_e32 v148, s84, v214
	s_barrier
	ds_read_b128 v[136:139], v148
	ds_read_b128 v[140:143], v148 offset:1024
	ds_read_b128 v[144:147], v148 offset:2048
	ds_read_b128 v[148:151], v148 offset:3072
	s_add_u32 s22, s52, 0x80000
	s_addc_u32 s23, s53, 0
	s_mov_b32 m0, s31
	ds_read_b128 v[152:155], v222 offset:32768
	ds_read_b128 v[156:159], v222 offset:33792
	ds_read_b128 v[186:189], v222 offset:34816
	ds_read_b128 v[190:193], v222 offset:35840
	ds_read_b128 v[194:197], v222 offset:36864
	ds_read_b128 v[198:201], v222 offset:37888
	ds_read_b128 v[202:205], v222 offset:38912
	ds_read_b128 v[206:209], v222 offset:39936
	global_load_lds_dwordx4 v180, s[22:23]
	s_mov_b32 m0, s58
	s_nop 0
	global_load_lds_dwordx4 v176, s[22:23]
	s_waitcnt lgkmcnt(8)
	s_barrier
	s_waitcnt lgkmcnt(0)
	s_waitcnt lgkmcnt(0)
	v_mfma_f32_16x16x32_f16 v[126:129], v[136:139], v[152:155], v[126:129]
	v_mfma_f32_16x16x32_f16 v[122:125], v[144:147], v[152:155], v[122:125]
	v_mfma_f32_16x16x32_f16 v[118:121], v[136:139], v[186:189], v[118:121]
	v_mfma_f32_16x16x32_f16 v[110:113], v[144:147], v[186:189], v[110:113]
	v_mfma_f32_16x16x32_f16 v[102:105], v[136:139], v[194:197], v[102:105]
	v_mfma_f32_16x16x32_f16 v[98:101], v[144:147], v[194:197], v[98:101]
	v_mfma_f32_16x16x32_f16 v[86:89], v[136:139], v[202:205], v[86:89]
	v_mfma_f32_16x16x32_f16 v[82:85], v[144:147], v[202:205], v[82:85]
	v_mfma_f32_16x16x32_f16 v[126:129], v[140:143], v[156:159], v[126:129]
	v_mfma_f32_16x16x32_f16 v[122:125], v[148:151], v[156:159], v[122:125]
	v_mfma_f32_16x16x32_f16 v[118:121], v[140:143], v[190:193], v[118:121]
	v_mfma_f32_16x16x32_f16 v[110:113], v[148:151], v[190:193], v[110:113]
	v_mfma_f32_16x16x32_f16 v[102:105], v[140:143], v[198:201], v[102:105]
	v_mfma_f32_16x16x32_f16 v[98:101], v[148:151], v[198:201], v[98:101]
	v_mfma_f32_16x16x32_f16 v[86:89], v[140:143], v[206:209], v[86:89]
	v_mfma_f32_16x16x32_f16 v[82:85], v[148:151], v[206:209], v[82:85]
	s_barrier
	s_add_i32 s85, 0, 0x1c000
	s_add_i32 s22, s84, s19
	v_add_u32_e32 v172, s85, v214
	s_mov_b32 m0, s22
	ds_read_b128 v[210:213], v172
	ds_read_b128 v[234:237], v172 offset:1024
	ds_read_b128 v[238:241], v172 offset:2048
	ds_read_b128 v[242:245], v172 offset:3072
	global_load_lds_dwordx4 v160, s[50:51]
	s_add_i32 m0, s22, 0x2000
	s_nop 0
	global_load_lds_dwordx4 v162, s[50:51]
	s_barrier
; #define PG8_STAGE(bufoff, gbase, voff) do { _Pragma("unroll") for (int _i = 0; _i < 2; ++_i) \
;         __builtin_amdgcn_global_load_lds((const unsigned*)((const char*)(gbase) + (voff)[_i]), (LAS unsigned*)(lds + (bufoff) + ldsw + _i * 8192), 16, 0, 0); } while (0)
; #define PG8_LDA(dst, b, h) do { _Pragma("unroll") for (int m = 0; m < 4; ++m) _Pragma("unroll") for (int k = 0; k < 2; ++k) dst[m][k] = *(const LAS f16x8*)(lds + PG8_SA(b, h) + aoff + m * 2048 + k * 1024); } while (0)
; #define PG8_MMA(ai, bj, At, Bt) do { __builtin_amdgcn_s_setprio(1); _Pragma("unroll") for (int m = 0; m < 4; ++m) _Pragma("unroll") for (int n = 0; n < 2; ++n) _Pragma("unroll") for (int k = 0; k < 2; ++k) \
;         acc[ai][bj][m][n] = __builtin_amdgcn_mfma_f32_16x16x32_f16(Bt[n][k], At[m][k], acc[ai][bj][m][n], 0, 0, 0); __builtin_amdgcn_s_setprio(0); } while (0)
; #define PG8_WAIT_V(n) asm volatile("s_waitcnt vmcnt(" #n ")" ::: "memory")
; #define PG8_WAIT_L(n) asm volatile("s_waitcnt lgkmcnt(" #n ")" ::: "memory")
; #define PG8_BAR __builtin_amdgcn_s_barrier()
; #define PG8_SCHED __builtin_amdgcn_sched_barrier(0)
; template <class Epi>
; __device__ __forceinline__ void gemm_phase(LAS unsigned char* lds, const Gemm g0, const StaticOrder& S, const Epi& E) {
;     ...
;             PG8_BAR; PG8_WAIT_L(0); PG8_MMA(0, 1, At, B1); PG8_BAR;
;             PG8_LDA(At, 1, 1); PG8_STAGE(PG8_SA(1, 0), a3, voffA);
;             PG8_BAR; PG8_WAIT_L(0); PG8_MMA(1, 0, At, B0); PG8_BAR; PG8_SCHED;
;             PG8_STAGE(PG8_SB(1, 1), b3 + hstep, voffB);
;             PG8_WAIT_V(6); PG8_BAR; PG8_MMA(1, 1, At, B1); PG8_BAR;
;         }
	s_waitcnt lgkmcnt(0)
	s_waitcnt lgkmcnt(0)
	v_mfma_f32_16x16x32_f16 v[114:117], v[210:213], v[152:155], v[114:117]
	v_mfma_f32_16x16x32_f16 v[106:109], v[238:241], v[152:155], v[106:109]
	v_mfma_f32_16x16x32_f16 v[94:97], v[210:213], v[186:189], v[94:97]
	v_mfma_f32_16x16x32_f16 v[90:93], v[238:241], v[186:189], v[90:93]
	v_mfma_f32_16x16x32_f16 v[78:81], v[210:213], v[194:197], v[78:81]
	v_mfma_f32_16x16x32_f16 v[74:77], v[238:241], v[194:197], v[74:77]
	v_mfma_f32_16x16x32_f16 v[70:73], v[210:213], v[202:205], v[70:73]
	v_mfma_f32_16x16x32_f16 v[66:69], v[238:241], v[202:205], v[66:69]
	v_mfma_f32_16x16x32_f16 v[114:117], v[234:237], v[156:159], v[114:117]
	v_mfma_f32_16x16x32_f16 v[106:109], v[242:245], v[156:159], v[106:109]
	v_mfma_f32_16x16x32_f16 v[94:97], v[234:237], v[190:193], v[94:97]
	v_mfma_f32_16x16x32_f16 v[90:93], v[242:245], v[190:193], v[90:93]
	v_mfma_f32_16x16x32_f16 v[78:81], v[234:237], v[198:201], v[78:81]
	v_mfma_f32_16x16x32_f16 v[74:77], v[242:245], v[198:201], v[74:77]
	v_mfma_f32_16x16x32_f16 v[70:73], v[234:237], v[206:209], v[70:73]
	v_mfma_f32_16x16x32_f16 v[66:69], v[242:245], v[206:209], v[66:69]
	s_mov_b32 m0, s59
	s_barrier
	ds_read_b128 v[152:155], v222 offset:49152
	ds_read_b128 v[156:159], v222 offset:50176
	ds_read_b128 v[186:189], v222 offset:51200
	ds_read_b128 v[190:193], v222 offset:52224
	ds_read_b128 v[194:197], v222 offset:53248
	ds_read_b128 v[198:201], v222 offset:54272
	ds_read_b128 v[202:205], v222 offset:55296
	ds_read_b128 v[206:209], v222 offset:56320
	global_load_lds_dwordx4 v164, s[52:53]
	s_mov_b32 m0, s61
	s_nop 0
	global_load_lds_dwordx4 v170, s[52:53]
	s_barrier
	s_waitcnt lgkmcnt(0)
	s_waitcnt lgkmcnt(0)
	v_mfma_f32_16x16x32_f16 v[62:65], v[136:139], v[152:155], v[62:65]
	v_mfma_f32_16x16x32_f16 v[58:61], v[144:147], v[152:155], v[58:61]
	v_mfma_f32_16x16x32_f16 v[54:57], v[136:139], v[186:189], v[54:57]
	v_mfma_f32_16x16x32_f16 v[50:53], v[144:147], v[186:189], v[50:53]
	v_mfma_f32_16x16x32_f16 v[38:41], v[136:139], v[194:197], v[38:41]
	v_mfma_f32_16x16x32_f16 v[30:33], v[144:147], v[194:197], v[30:33]
	v_mfma_f32_16x16x32_f16 v[22:25], v[136:139], v[202:205], v[22:25]
	v_mfma_f32_16x16x32_f16 v[18:21], v[144:147], v[202:205], v[18:21]
	v_mfma_f32_16x16x32_f16 v[62:65], v[140:143], v[156:159], v[62:65]
	v_mfma_f32_16x16x32_f16 v[58:61], v[148:151], v[156:159], v[58:61]
	v_mfma_f32_16x16x32_f16 v[54:57], v[140:143], v[190:193], v[54:57]
	v_mfma_f32_16x16x32_f16 v[50:53], v[148:151], v[190:193], v[50:53]
	v_mfma_f32_16x16x32_f16 v[38:41], v[140:143], v[198:201], v[38:41]
	v_mfma_f32_16x16x32_f16 v[30:33], v[148:151], v[198:201], v[30:33]
	v_mfma_f32_16x16x32_f16 v[22:25], v[140:143], v[206:209], v[22:25]
	v_mfma_f32_16x16x32_f16 v[18:21], v[148:151], v[206:209], v[18:21]
	s_barrier
	s_add_u32 s22, s50, 0x80080
	s_addc_u32 s23, s51, 0
	s_add_i32 s50, s85, s19
	s_mov_b32 m0, s50
	s_nop 0
	global_load_lds_dwordx4 v178, s[22:23]
	v_lshl_add_u64 v[136:137], s[22:23], 0, v[174:175]
	s_add_i32 m0, s50, 0x2000
	s_nop 0
	global_load_lds_dwordx4 v[136:137], off
	s_waitcnt vmcnt(6)
	s_barrier
	v_mfma_f32_16x16x32_f16 v[46:49], v[210:213], v[152:155], v[46:49]
	v_mfma_f32_16x16x32_f16 v[42:45], v[238:241], v[152:155], v[42:45]
	v_mfma_f32_16x16x32_f16 v[34:37], v[210:213], v[186:189], v[34:37]
	v_mfma_f32_16x16x32_f16 v[26:29], v[238:241], v[186:189], v[26:29]
	v_mfma_f32_16x16x32_f16 v[14:17], v[210:213], v[194:197], v[14:17]
	v_mfma_f32_16x16x32_f16 v[10:13], v[238:241], v[194:197], v[10:13]
	v_mfma_f32_16x16x32_f16 v[6:9], v[210:213], v[202:205], v[6:9]
	v_mfma_f32_16x16x32_f16 v[2:5], v[238:241], v[202:205], v[2:5]
	v_mfma_f32_16x16x32_f16 v[46:49], v[234:237], v[156:159], v[46:49]
	v_mfma_f32_16x16x32_f16 v[42:45], v[242:245], v[156:159], v[42:45]
	v_mfma_f32_16x16x32_f16 v[34:37], v[234:237], v[190:193], v[34:37]
	v_mfma_f32_16x16x32_f16 v[26:29], v[242:245], v[190:193], v[26:29]
	v_mfma_f32_16x16x32_f16 v[14:17], v[234:237], v[198:201], v[14:17]
	v_mfma_f32_16x16x32_f16 v[10:13], v[242:245], v[198:201], v[10:13]
	v_mfma_f32_16x16x32_f16 v[6:9], v[234:237], v[206:209], v[6:9]
	v_mfma_f32_16x16x32_f16 v[2:5], v[242:245], v[206:209], v[2:5]
	s_add_i32 s83, s83, 2
	s_add_u32 s24, s24, 0x100
	s_addc_u32 s25, s25, 0
	s_add_u32 s0, s0, 0x100
	s_addc_u32 s1, s1, 0
	s_cmp_gt_u32 s83, 29
	s_barrier
	s_cbranch_scc1 .LBB0_201

;     __device__ __forceinline__ void prefetch(const Unit& u, int wr, int wc, int lane) const { lnfold_prefetch(vl, stats, gW, bW, u, wr, wc, lane); }
;     __device__ __forceinline__ void prefetch(const Unit& u, int wr, int wc, int lane) const { lnfold_prefetch(vl, stats, gW, bW, u, wr, wc, lane); }
; #define PG8_STAGE(bufoff, gbase, voff) do { _Pragma("unroll") for (int _i = 0; _i < 2; ++_i) \
;         __builtin_amdgcn_global_load_lds((const unsigned*)((const char*)(gbase) + (voff)[_i]), (LAS unsigned*)(lds + (bufoff) + ldsw + _i * 8192), 16, 0, 0); } while (0)
; #define PG8_LDA(dst, b, h) do { _Pragma("unroll") for (int m = 0; m < 4; ++m) _Pragma("unroll") for (int k = 0; k < 2; ++k) dst[m][k] = *(const LAS f16x8*)(lds + PG8_SA(b, h) + aoff + m * 2048 + k * 1024); } while (0)
; #define PG8_LDB(dst, b, h) do { _Pragma("unroll") for (int n = 0; n < 2; ++n) _Pragma("unroll") for (int k = 0; k < 2; ++k) dst[n][k] = *(const LAS f16x8*)(lds + PG8_SB(b, h) + boff + n * 2048 + k * 1024); } while (0)
; template <class Epi>
; __device__ __forceinline__ void gemm_phase(LAS unsigned char* lds, const Gemm g0, const StaticOrder& S, const Epi& E) {
;     ...
;         const char* nA = has_next ? (const char*)g.A + (size_t)nxt.pm * tstep : cA; const char* nB = has_next ? (const char*)g.Bt + (size_t)nxt.pn * tstep : cB;
;         for (int t = 0; t < nt; t += 2) {
;             const bool last = (t == nt - 2);
;             if (Epi::PREF && last) E.prefetch(cur, wr, wc, lane);
;             const char* a1 = cA + (size_t)(t + 1) * kstep;
;             const char* a2 = last ? nA : cA + (size_t)(t + 2) * kstep; const char* b2 = last ? nB : cB + (size_t)(t + 2) * kstep;
;             const char* a3 = a2 + kstep; const char* b3 = b2 + kstep;
;             PG8_LDB(B0, 0, 0); PG8_SCHED; PG8_LDA(At, 0, 0); PG8_STAGE(PG8_SA(1, 1), a1 + hstep, voffA);
;             PG8_WAIT_L(8); PG8_BAR; PG8_WAIT_L(0); PG8_MMA(0, 0, At, B0); PG8_BAR; PG8_SCHED;
;             PG8_LDB(B1, 0, 1); PG8_STAGE(PG8_SB(0, 0), b2, voffB);
;             PG8_BAR; PG8_WAIT_L(0); PG8_MMA(0, 1, At, B1); PG8_BAR;
;             PG8_LDA(At, 0, 1); PG8_STAGE(PG8_SA(0, 0), a2, voffA);
;             PG8_BAR; PG8_WAIT_L(0); PG8_MMA(1, 0, At, B0); PG8_BAR; PG8_SCHED;
;             PG8_STAGE(PG8_SB(0, 1), b2 + hstep, voffB);
;             PG8_WAIT_V(6); PG8_BAR; PG8_MMA(1, 1, At, B1); PG8_BAR;
.LBB0_302:
	s_add_u32 s22, s6, 0xfff80080
	s_addc_u32 s23, s7, -1
	s_add_i32 s59, 0, 0x10000
	v_add_u32_e32 v146, s59, v148
	ds_read_b128 v[142:145], v146
	ds_read_b128 v[152:155], v146 offset:1024
	ds_read_b128 v[156:159], v146 offset:2048
	ds_read_b128 v[174:177], v146 offset:3072
	s_cmp_eq_u32 s58, 28
	s_cselect_b32 s37, s15, s23
	s_cselect_b32 s36, s52, s22
	s_cselect_b32 s35, s13, s53
	s_cselect_b32 s34, s24, s25
	s_add_i32 m0, s28, 0xc000
	ds_read_b128 v[178:181], v150
	ds_read_b128 v[182:185], v150 offset:1024
	ds_read_b128 v[186:189], v150 offset:2048
	ds_read_b128 v[190:193], v150 offset:3072
	ds_read_b128 v[194:197], v150 offset:4096
	ds_read_b128 v[198:201], v150 offset:5120
	ds_read_b128 v[202:205], v150 offset:6144
	ds_read_b128 v[206:209], v150 offset:7168
	global_load_lds_dwordx4 v140, s[6:7]
	s_add_i32 m0, s28, 0xe000
	s_nop 0
	global_load_lds_dwordx4 v138, s[6:7]
	s_waitcnt lgkmcnt(8)
	s_barrier
	s_waitcnt lgkmcnt(0)
	s_waitcnt lgkmcnt(0)
	v_mfma_f32_16x16x32_f16 v[126:129], v[142:145], v[178:181], v[126:129]
	v_mfma_f32_16x16x32_f16 v[122:125], v[156:159], v[178:181], v[122:125]
	v_mfma_f32_16x16x32_f16 v[110:113], v[142:145], v[186:189], v[110:113]
	v_mfma_f32_16x16x32_f16 v[106:109], v[156:159], v[186:189], v[106:109]
	v_mfma_f32_16x16x32_f16 v[94:97], v[142:145], v[194:197], v[94:97]
	v_mfma_f32_16x16x32_f16 v[90:93], v[156:159], v[194:197], v[90:93]
	v_mfma_f32_16x16x32_f16 v[78:81], v[142:145], v[202:205], v[78:81]
	v_mfma_f32_16x16x32_f16 v[74:77], v[156:159], v[202:205], v[74:77]
	v_mfma_f32_16x16x32_f16 v[126:129], v[152:155], v[182:185], v[126:129]
	v_mfma_f32_16x16x32_f16 v[122:125], v[174:177], v[182:185], v[122:125]
	v_mfma_f32_16x16x32_f16 v[110:113], v[152:155], v[190:193], v[110:113]
	v_mfma_f32_16x16x32_f16 v[106:109], v[174:177], v[190:193], v[106:109]
	v_mfma_f32_16x16x32_f16 v[94:97], v[152:155], v[198:201], v[94:97]
	v_mfma_f32_16x16x32_f16 v[90:93], v[174:177], v[198:201], v[90:93]
	v_mfma_f32_16x16x32_f16 v[78:81], v[152:155], v[206:209], v[78:81]
	v_mfma_f32_16x16x32_f16 v[74:77], v[174:177], v[206:209], v[74:77]
	s_barrier
	s_add_i32 s61, 0, 0x14000
	v_add_u32_e32 v146, s61, v148
	s_add_i32 s22, s59, s19
	ds_read_b128 v[210:213], v146
	ds_read_b128 v[234:237], v146 offset:1024
	ds_read_b128 v[238:241], v146 offset:2048
	ds_read_b128 v[242:245], v146 offset:3072
	v_add_u32_e32 v146, 0x80, v134
	s_mov_b32 m0, s22
	v_add_u32_e32 v160, 0x80, v130
	global_load_lds_dwordx4 v134, s[34:35]
	s_add_i32 m0, s22, 0x2000
	s_nop 0
	global_load_lds_dwordx4 v130, s[34:35]
	s_barrier
	s_waitcnt lgkmcnt(0)
	s_waitcnt lgkmcnt(0)
	v_mfma_f32_16x16x32_f16 v[118:121], v[210:213], v[178:181], v[118:121]
	v_mfma_f32_16x16x32_f16 v[114:117], v[238:241], v[178:181], v[114:117]
	v_mfma_f32_16x16x32_f16 v[102:105], v[210:213], v[186:189], v[102:105]
	v_mfma_f32_16x16x32_f16 v[98:101], v[238:241], v[186:189], v[98:101]
	v_mfma_f32_16x16x32_f16 v[86:89], v[210:213], v[194:197], v[86:89]
	v_mfma_f32_16x16x32_f16 v[82:85], v[238:241], v[194:197], v[82:85]
	v_mfma_f32_16x16x32_f16 v[70:73], v[210:213], v[202:205], v[70:73]
	v_mfma_f32_16x16x32_f16 v[66:69], v[238:241], v[202:205], v[66:69]
	v_mfma_f32_16x16x32_f16 v[118:121], v[234:237], v[182:185], v[118:121]
	v_mfma_f32_16x16x32_f16 v[114:117], v[242:245], v[182:185], v[114:117]
	v_mfma_f32_16x16x32_f16 v[102:105], v[234:237], v[190:193], v[102:105]
	v_mfma_f32_16x16x32_f16 v[98:101], v[242:245], v[190:193], v[98:101]
	v_mfma_f32_16x16x32_f16 v[86:89], v[234:237], v[198:201], v[86:89]
	v_mfma_f32_16x16x32_f16 v[82:85], v[242:245], v[198:201], v[82:85]
	v_mfma_f32_16x16x32_f16 v[70:73], v[234:237], v[206:209], v[70:73]
	v_mfma_f32_16x16x32_f16 v[66:69], v[242:245], v[206:209], v[66:69]
	s_mov_b32 m0, s28
	v_add_u32_e32 v162, 0x80, v136
	s_barrier
	ds_read_b128 v[178:181], v150 offset:16384
	ds_read_b128 v[182:185], v150 offset:17408
	ds_read_b128 v[186:189], v150 offset:18432
	ds_read_b128 v[190:193], v150 offset:19456
	ds_read_b128 v[194:197], v150 offset:20480
	ds_read_b128 v[198:201], v150 offset:21504
	ds_read_b128 v[202:205], v150 offset:22528
	ds_read_b128 v[206:209], v150 offset:23552
	global_load_lds_dwordx4 v136, s[36:37]
	v_add_u32_e32 v164, 0x80, v132
	s_mov_b32 m0, s29
	s_nop 0
	global_load_lds_dwordx4 v132, s[36:37]
	s_barrier
	s_waitcnt lgkmcnt(0)
	s_waitcnt lgkmcnt(0)
	v_mfma_f32_16x16x32_f16 v[62:65], v[142:145], v[178:181], v[62:65]
	v_mfma_f32_16x16x32_f16 v[58:61], v[156:159], v[178:181], v[58:61]
	v_mfma_f32_16x16x32_f16 v[46:49], v[142:145], v[186:189], v[46:49]
	v_mfma_f32_16x16x32_f16 v[42:45], v[156:159], v[186:189], v[42:45]
	v_mfma_f32_16x16x32_f16 v[30:33], v[142:145], v[194:197], v[30:33]
	v_mfma_f32_16x16x32_f16 v[26:29], v[156:159], v[194:197], v[26:29]
	v_mfma_f32_16x16x32_f16 v[14:17], v[142:145], v[202:205], v[14:17]
	v_mfma_f32_16x16x32_f16 v[10:13], v[156:159], v[202:205], v[10:13]
	v_mfma_f32_16x16x32_f16 v[62:65], v[152:155], v[182:185], v[62:65]
	v_mfma_f32_16x16x32_f16 v[58:61], v[174:177], v[182:185], v[58:61]
	v_mfma_f32_16x16x32_f16 v[46:49], v[152:155], v[190:193], v[46:49]
	v_mfma_f32_16x16x32_f16 v[42:45], v[174:177], v[190:193], v[42:45]
	v_mfma_f32_16x16x32_f16 v[30:33], v[152:155], v[198:201], v[30:33]
	v_mfma_f32_16x16x32_f16 v[26:29], v[174:177], v[198:201], v[26:29]
	v_mfma_f32_16x16x32_f16 v[14:17], v[152:155], v[206:209], v[14:17]
	v_mfma_f32_16x16x32_f16 v[10:13], v[174:177], v[206:209], v[10:13]
	s_barrier
	s_add_u32 s22, s34, 0x80000
	s_addc_u32 s23, s35, 0
	s_add_i32 s59, s61, s19
	s_mov_b32 m0, s59
	s_nop 0
	global_load_lds_dwordx4 v134, s[22:23]
	s_add_i32 m0, s59, 0x2000
	s_nop 0
	global_load_lds_dwordx4 v130, s[22:23]
	s_waitcnt vmcnt(6)
	s_barrier
; #define PG8_STAGE(bufoff, gbase, voff) do { _Pragma("unroll") for (int _i = 0; _i < 2; ++_i) \
;         __builtin_amdgcn_global_load_lds((const unsigned*)((const char*)(gbase) + (voff)[_i]), (LAS unsigned*)(lds + (bufoff) + ldsw + _i * 8192), 16, 0, 0); } while (0)
; #define PG8_LDA(dst, b, h) do { _Pragma("unroll") for (int m = 0; m < 4; ++m) _Pragma("unroll") for (int k = 0; k < 2; ++k) dst[m][k] = *(const LAS f16x8*)(lds + PG8_SA(b, h) + aoff + m * 2048 + k * 1024); } while (0)
; #define PG8_LDB(dst, b, h) do { _Pragma("unroll") for (int n = 0; n < 2; ++n) _Pragma("unroll") for (int k = 0; k < 2; ++k) dst[n][k] = *(const LAS f16x8*)(lds + PG8_SB(b, h) + boff + n * 2048 + k * 1024); } while (0)
; #define PG8_MMA(ai, bj, At, Bt) do { __builtin_amdgcn_s_setprio(1); _Pragma("unroll") for (int m = 0; m < 4; ++m) _Pragma("unroll") for (int n = 0; n < 2; ++n) _Pragma("unroll") for (int k = 0; k < 2; ++k) \
;         acc[ai][bj][m][n] = __builtin_amdgcn_mfma_f32_16x16x32_f16(Bt[n][k], At[m][k], acc[ai][bj][m][n], 0, 0, 0); __builtin_amdgcn_s_setprio(0); } while (0)
; #define PG8_WAIT_V(n) asm volatile("s_waitcnt vmcnt(" #n ")" ::: "memory")
; #define PG8_WAIT_L(n) asm volatile("s_waitcnt lgkmcnt(" #n ")" ::: "memory")
; #define PG8_BAR __builtin_amdgcn_s_barrier()
; #define PG8_SCHED __builtin_amdgcn_sched_barrier(0)
; template <class Epi>
; __device__ __forceinline__ void gemm_phase(LAS unsigned char* lds, const Gemm g0, const StaticOrder& S, const Epi& E) {
;     ...
;             PG8_WAIT_V(6); PG8_BAR; PG8_MMA(1, 1, At, B1); PG8_BAR;
;             PG8_LDB(B0, 1, 0); PG8_SCHED; PG8_LDA(At, 1, 0); PG8_STAGE(PG8_SA(0, 1), a2 + hstep, voffA);
;             PG8_WAIT_L(8); PG8_BAR; PG8_WAIT_L(0); PG8_MMA(0, 0, At, B0); PG8_BAR; PG8_SCHED;
;             PG8_LDB(B1, 1, 1); PG8_STAGE(PG8_SB(1, 0), b3, voffB);
;             PG8_BAR; PG8_WAIT_L(0); PG8_MMA(0, 1, At, B1); PG8_BAR;
;             PG8_LDA(At, 1, 1); PG8_STAGE(PG8_SA(1, 0), a3, voffA);
	v_mfma_f32_16x16x32_f16 v[54:57], v[210:213], v[178:181], v[54:57]
	v_mfma_f32_16x16x32_f16 v[50:53], v[238:241], v[178:181], v[50:53]
	v_mfma_f32_16x16x32_f16 v[38:41], v[210:213], v[186:189], v[38:41]
	v_mfma_f32_16x16x32_f16 v[34:37], v[238:241], v[186:189], v[34:37]
	v_mfma_f32_16x16x32_f16 v[22:25], v[210:213], v[194:197], v[22:25]
	v_mfma_f32_16x16x32_f16 v[18:21], v[238:241], v[194:197], v[18:21]
	v_mfma_f32_16x16x32_f16 v[6:9], v[210:213], v[202:205], v[6:9]
	v_mfma_f32_16x16x32_f16 v[2:5], v[238:241], v[202:205], v[2:5]
	v_mfma_f32_16x16x32_f16 v[54:57], v[234:237], v[182:185], v[54:57]
	v_mfma_f32_16x16x32_f16 v[50:53], v[242:245], v[182:185], v[50:53]
	v_mfma_f32_16x16x32_f16 v[38:41], v[234:237], v[190:193], v[38:41]
	v_mfma_f32_16x16x32_f16 v[34:37], v[242:245], v[190:193], v[34:37]
	v_mfma_f32_16x16x32_f16 v[22:25], v[234:237], v[198:201], v[22:25]
	v_mfma_f32_16x16x32_f16 v[18:21], v[242:245], v[198:201], v[18:21]
	v_mfma_f32_16x16x32_f16 v[6:9], v[234:237], v[206:209], v[6:9]
	v_mfma_f32_16x16x32_f16 v[2:5], v[242:245], v[206:209], v[2:5]
	s_add_i32 s59, 0, 0x18000
	v_add_u32_e32 v151, s59, v148
	s_barrier
	ds_read_b128 v[142:145], v151
	ds_read_b128 v[152:155], v151 offset:1024
	ds_read_b128 v[156:159], v151 offset:2048
	ds_read_b128 v[174:177], v151 offset:3072
	s_add_u32 s22, s36, 0x80000
	s_addc_u32 s23, s37, 0
	s_mov_b32 m0, s31
	ds_read_b128 v[178:181], v150 offset:32768
	ds_read_b128 v[182:185], v150 offset:33792
	ds_read_b128 v[186:189], v150 offset:34816
	ds_read_b128 v[190:193], v150 offset:35840
	ds_read_b128 v[194:197], v150 offset:36864
	ds_read_b128 v[198:201], v150 offset:37888
	ds_read_b128 v[202:205], v150 offset:38912
	ds_read_b128 v[206:209], v150 offset:39936
	global_load_lds_dwordx4 v136, s[22:23]
	v_lshl_add_u64 v[170:171], s[22:23], 0, v[132:133]
	s_mov_b32 m0, s38
	s_nop 0
	global_load_lds_dwordx4 v[170:171], off
	s_waitcnt lgkmcnt(8)
	s_barrier
	s_waitcnt lgkmcnt(0)
	s_waitcnt lgkmcnt(0)
	v_mfma_f32_16x16x32_f16 v[126:129], v[142:145], v[178:181], v[126:129]
	v_mfma_f32_16x16x32_f16 v[122:125], v[156:159], v[178:181], v[122:125]
	v_mfma_f32_16x16x32_f16 v[110:113], v[142:145], v[186:189], v[110:113]
	v_mfma_f32_16x16x32_f16 v[106:109], v[156:159], v[186:189], v[106:109]
	v_mfma_f32_16x16x32_f16 v[94:97], v[142:145], v[194:197], v[94:97]
	v_mfma_f32_16x16x32_f16 v[90:93], v[156:159], v[194:197], v[90:93]
	v_mfma_f32_16x16x32_f16 v[78:81], v[142:145], v[202:205], v[78:81]
	v_mfma_f32_16x16x32_f16 v[74:77], v[156:159], v[202:205], v[74:77]
	v_mfma_f32_16x16x32_f16 v[126:129], v[152:155], v[182:185], v[126:129]
	v_mfma_f32_16x16x32_f16 v[122:125], v[174:177], v[182:185], v[122:125]
	v_mfma_f32_16x16x32_f16 v[110:113], v[152:155], v[190:193], v[110:113]
	v_mfma_f32_16x16x32_f16 v[106:109], v[174:177], v[190:193], v[106:109]
	v_mfma_f32_16x16x32_f16 v[94:97], v[152:155], v[198:201], v[94:97]
	v_mfma_f32_16x16x32_f16 v[90:93], v[174:177], v[198:201], v[90:93]
	v_mfma_f32_16x16x32_f16 v[78:81], v[152:155], v[206:209], v[78:81]
	v_mfma_f32_16x16x32_f16 v[74:77], v[174:177], v[206:209], v[74:77]
	s_barrier
	s_add_i32 s61, 0, 0x1c000
	s_add_i32 s22, s59, s19
	v_add_u32_e32 v151, s61, v148
	s_mov_b32 m0, s22
	ds_read_b128 v[210:213], v151
	ds_read_b128 v[234:237], v151 offset:1024
	ds_read_b128 v[238:241], v151 offset:2048
	ds_read_b128 v[242:245], v151 offset:3072
	global_load_lds_dwordx4 v146, s[34:35]
	s_add_i32 m0, s22, 0x2000
	s_nop 0
	global_load_lds_dwordx4 v160, s[34:35]
	s_barrier
	s_waitcnt lgkmcnt(0)
	s_waitcnt lgkmcnt(0)
	v_mfma_f32_16x16x32_f16 v[118:121], v[210:213], v[178:181], v[118:121]
	v_mfma_f32_16x16x32_f16 v[114:117], v[238:241], v[178:181], v[114:117]
	v_mfma_f32_16x16x32_f16 v[102:105], v[210:213], v[186:189], v[102:105]
	v_mfma_f32_16x16x32_f16 v[98:101], v[238:241], v[186:189], v[98:101]
	v_mfma_f32_16x16x32_f16 v[86:89], v[210:213], v[194:197], v[86:89]
	v_mfma_f32_16x16x32_f16 v[82:85], v[238:241], v[194:197], v[82:85]
	v_mfma_f32_16x16x32_f16 v[70:73], v[210:213], v[202:205], v[70:73]
	v_mfma_f32_16x16x32_f16 v[66:69], v[238:241], v[202:205], v[66:69]
	v_mfma_f32_16x16x32_f16 v[118:121], v[234:237], v[182:185], v[118:121]
	v_mfma_f32_16x16x32_f16 v[114:117], v[242:245], v[182:185], v[114:117]
	v_mfma_f32_16x16x32_f16 v[102:105], v[234:237], v[190:193], v[102:105]
	v_mfma_f32_16x16x32_f16 v[98:101], v[242:245], v[190:193], v[98:101]
	v_mfma_f32_16x16x32_f16 v[86:89], v[234:237], v[198:201], v[86:89]
	v_mfma_f32_16x16x32_f16 v[82:85], v[242:245], v[198:201], v[82:85]
	v_mfma_f32_16x16x32_f16 v[70:73], v[234:237], v[206:209], v[70:73]
	v_mfma_f32_16x16x32_f16 v[66:69], v[242:245], v[206:209], v[66:69]
	s_mov_b32 m0, s39
	s_barrier
	ds_read_b128 v[178:181], v150 offset:49152
	ds_read_b128 v[182:185], v150 offset:50176
	ds_read_b128 v[186:189], v150 offset:51200
	ds_read_b128 v[190:193], v150 offset:52224
	ds_read_b128 v[194:197], v150 offset:53248
	ds_read_b128 v[198:201], v150 offset:54272
	ds_read_b128 v[202:205], v150 offset:55296
	ds_read_b128 v[206:209], v150 offset:56320
	global_load_lds_dwordx4 v162, s[36:37]
	s_mov_b32 m0, s48
	s_nop 0
	global_load_lds_dwordx4 v164, s[36:37]
	s_barrier
; __device__ __forceinline__ float gelu_tanh(float x) { const float y = 1.5957691216057308f * (x + 0.044715f * x * x * x); return x * fast_rcp(1.0f + __expf(-y)); }
; #define PG8_STAGE(bufoff, gbase, voff) do { _Pragma("unroll") for (int _i = 0; _i < 2; ++_i) \
;         __builtin_amdgcn_global_load_lds((const unsigned*)((const char*)(gbase) + (voff)[_i]), (LAS unsigned*)(lds + (bufoff) + ldsw + _i * 8192), 16, 0, 0); } while (0)
; #define PG8_MMA(ai, bj, At, Bt) do { __builtin_amdgcn_s_setprio(1); _Pragma("unroll") for (int m = 0; m < 4; ++m) _Pragma("unroll") for (int n = 0; n < 2; ++n) _Pragma("unroll") for (int k = 0; k < 2; ++k) \
;         acc[ai][bj][m][n] = __builtin_amdgcn_mfma_f32_16x16x32_f16(Bt[n][k], At[m][k], acc[ai][bj][m][n], 0, 0, 0); __builtin_amdgcn_s_setprio(0); } while (0)
; #define PG8_WAIT_V(n) asm volatile("s_waitcnt vmcnt(" #n ")" ::: "memory")
; #define PG8_WAIT_L(n) asm volatile("s_waitcnt lgkmcnt(" #n ")" ::: "memory")
; #define PG8_BAR __builtin_amdgcn_s_barrier()
; #define PG8_SCHED __builtin_amdgcn_sched_barrier(0)
;     __device__ __forceinline__ void operator()(f32x4 (&acc)[2][2][4][2], const Unit& u, int wr, int wc, int fr, int fq) const {
;         const bool isy = u.pn < 8; h16* dst = isy ? ybr : xpre; const int colb = (isy ? u.pn : u.pn - 8) * BM + wc * 32 + 8 * fq;
;         const int row0 = u.pm * BM + wr * 64 + fr;
; #pragma unroll
;         for (int ai = 0; ai < 2; ++ai)
; #pragma unroll
;             for (int m = 0; m < 4; ++m) { h16* rowp = dst + (size_t)(row0 + ai * HALF + m * 16) * DM + colb;
; #pragma unroll
;                 for (int bj = 0; bj < 2; ++bj) { f32x4 v0 = acc[ai][bj][m][0], v1 = acc[ai][bj][m][1];
;                     if (isy) {
; #pragma unroll
;                         for (int j = 0; j < 4; ++j) { v0[j] = gelu_tanh(v0[j]); v1[j] = gelu_tanh(v1[j]); } }
; template <class Epi>
; __device__ __forceinline__ void gemm_phase(LAS unsigned char* lds, const Gemm g0, const StaticOrder& S, const Epi& E) {
;     ...
;             PG8_BAR; PG8_WAIT_L(0); PG8_MMA(1, 0, At, B0); PG8_BAR; PG8_SCHED;
;             PG8_STAGE(PG8_SB(1, 1), b3 + hstep, voffB);
;             PG8_WAIT_V(6); PG8_BAR; PG8_MMA(1, 1, At, B1); PG8_BAR;
;         }
	s_waitcnt lgkmcnt(0)
	s_waitcnt lgkmcnt(0)
	v_mfma_f32_16x16x32_f16 v[62:65], v[142:145], v[178:181], v[62:65]
	v_mfma_f32_16x16x32_f16 v[58:61], v[156:159], v[178:181], v[58:61]
	v_mfma_f32_16x16x32_f16 v[46:49], v[142:145], v[186:189], v[46:49]
	v_mfma_f32_16x16x32_f16 v[42:45], v[156:159], v[186:189], v[42:45]
	v_mfma_f32_16x16x32_f16 v[30:33], v[142:145], v[194:197], v[30:33]
	v_mfma_f32_16x16x32_f16 v[26:29], v[156:159], v[194:197], v[26:29]
	v_mfma_f32_16x16x32_f16 v[14:17], v[142:145], v[202:205], v[14:17]
	v_mfma_f32_16x16x32_f16 v[10:13], v[156:159], v[202:205], v[10:13]
	v_mfma_f32_16x16x32_f16 v[62:65], v[152:155], v[182:185], v[62:65]
	v_mfma_f32_16x16x32_f16 v[58:61], v[174:177], v[182:185], v[58:61]
	v_mfma_f32_16x16x32_f16 v[46:49], v[152:155], v[190:193], v[46:49]
	v_mfma_f32_16x16x32_f16 v[42:45], v[174:177], v[190:193], v[42:45]
	v_mfma_f32_16x16x32_f16 v[30:33], v[152:155], v[198:201], v[30:33]
	v_mfma_f32_16x16x32_f16 v[26:29], v[174:177], v[198:201], v[26:29]
	v_mfma_f32_16x16x32_f16 v[14:17], v[152:155], v[206:209], v[14:17]
	v_mfma_f32_16x16x32_f16 v[10:13], v[174:177], v[206:209], v[10:13]
	s_barrier
	s_add_u32 s22, s34, 0x80080
	s_addc_u32 s23, s35, 0
	s_add_i32 s34, s61, s19
	s_mov_b32 m0, s34
	s_nop 0
	global_load_lds_dwordx4 v134, s[22:23]
	s_add_i32 m0, s34, 0x2000
	s_nop 0
	global_load_lds_dwordx4 v130, s[22:23]
	s_waitcnt vmcnt(6)
	s_barrier
	v_mfma_f32_16x16x32_f16 v[54:57], v[210:213], v[178:181], v[54:57]
	v_mfma_f32_16x16x32_f16 v[50:53], v[238:241], v[178:181], v[50:53]
	v_mfma_f32_16x16x32_f16 v[38:41], v[210:213], v[186:189], v[38:41]
	v_mfma_f32_16x16x32_f16 v[34:37], v[238:241], v[186:189], v[34:37]
	v_mfma_f32_16x16x32_f16 v[22:25], v[210:213], v[194:197], v[22:25]
	v_mfma_f32_16x16x32_f16 v[18:21], v[238:241], v[194:197], v[18:21]
	v_mfma_f32_16x16x32_f16 v[6:9], v[210:213], v[202:205], v[6:9]
	v_mfma_f32_16x16x32_f16 v[2:5], v[238:241], v[202:205], v[2:5]
	v_mfma_f32_16x16x32_f16 v[54:57], v[234:237], v[182:185], v[54:57]
	v_mfma_f32_16x16x32_f16 v[50:53], v[242:245], v[182:185], v[50:53]
	v_mfma_f32_16x16x32_f16 v[38:41], v[234:237], v[190:193], v[38:41]
	v_mfma_f32_16x16x32_f16 v[34:37], v[242:245], v[190:193], v[34:37]
	v_mfma_f32_16x16x32_f16 v[22:25], v[234:237], v[198:201], v[22:25]
	v_mfma_f32_16x16x32_f16 v[18:21], v[242:245], v[198:201], v[18:21]
	v_mfma_f32_16x16x32_f16 v[6:9], v[234:237], v[206:209], v[6:9]
	v_mfma_f32_16x16x32_f16 v[2:5], v[242:245], v[206:209], v[2:5]
	s_add_i32 s58, s58, 2
	s_add_u32 s25, s25, 0x100
	s_addc_u32 s53, s53, 0
	s_add_u32 s6, s6, 0x100
	s_addc_u32 s7, s7, 0
	s_cmp_gt_u32 s58, 29
	s_barrier
	s_cbranch_scc0 .LBB0_302
	s_cmp_lt_i32 s51, 8
	s_cselect_b64 s[34:35], -1, 0
	s_cmp_gt_i32 s51, 7
	s_cbranch_scc1 .LBB0_305
	v_mul_f32_e32 v143, 0x3d372713, v122
	v_mul_f32_e32 v143, v122, v143
	v_fma_f32 v143, v122, v143, v122
	v_mul_f32_e32 v143, 0xbfcc422a, v143
	v_mul_f32_e32 v143, 0x3fb8aa3b, v143
	v_exp_f32_e32 v143, v143
	v_mul_f32_e32 v142, 0x3d372713, v126
	v_mul_f32_e32 v142, v126, v142
	v_fma_f32 v142, v126, v142, v126
	v_add_f32_e32 v143, 1.0, v143
	v_rcp_f32_e32 v144, v143
	v_mul_f32_e32 v143, 0x3d372713, v127
	v_mul_f32_e32 v143, v127, v143
	v_fma_f32 v143, v127, v143, v127
	v_mul_f32_e32 v142, 0xbfcc422a, v142
	v_mul_f32_e32 v143, 0xbfcc422a, v143
	v_mul_f32_e32 v142, 0x3fb8aa3b, v142
	v_mul_f32_e32 v143, 0x3fb8aa3b, v143
	v_mul_f32_e32 v147, 0x3d372713, v124
	v_exp_f32_e32 v142, v142
	v_exp_f32_e32 v143, v143
	v_mul_f32_e32 v147, v124, v147
	v_fma_f32 v147, v124, v147, v124
	v_mul_f32_e32 v147, 0xbfcc422a, v147
	v_mul_f32_e32 v147, 0x3fb8aa3b, v147
	v_add_f32_e32 v142, 1.0, v142
	v_add_f32_e32 v143, 1.0, v143
	v_exp_f32_e32 v147, v147
	v_rcp_f32_e32 v142, v142
	v_rcp_f32_e32 v143, v143
	v_mul_f32_e32 v145, 0x3d372713, v123
	v_add_f32_e32 v147, 1.0, v147
	v_mul_f32_e32 v146, 0x3d372713, v128
	v_rcp_f32_e32 v152, v147
	v_mul_f32_e32 v147, 0x3d372713, v129
	v_pk_mul_f32 v[126:127], v[126:127], v[142:143]
	v_mul_f32_e32 v142, 0x3d372713, v125
	v_mul_f32_e32 v145, v123, v145
	v_mul_f32_e32 v146, v128, v146
	v_mul_f32_e32 v147, v129, v147
	v_mul_f32_e32 v142, v125, v142
	v_fma_f32 v145, v123, v145, v123
	v_fma_f32 v146, v128, v146, v128
	v_fma_f32 v147, v129, v147, v129
	v_fma_f32 v142, v125, v142, v125
	v_mul_f32_e32 v145, 0xbfcc422a, v145
	v_mul_f32_e32 v146, 0xbfcc422a, v146
	v_mul_f32_e32 v147, 0xbfcc422a, v147
	v_mul_f32_e32 v142, 0xbfcc422a, v142
	v_mul_f32_e32 v145, 0x3fb8aa3b, v145
	v_mul_f32_e32 v146, 0x3fb8aa3b, v146
	v_mul_f32_e32 v147, 0x3fb8aa3b, v147
	v_mul_f32_e32 v142, 0x3fb8aa3b, v142
	v_exp_f32_e32 v145, v145
	v_exp_f32_e32 v146, v146
	v_exp_f32_e32 v147, v147
	v_exp_f32_e32 v142, v142
	v_add_f32_e32 v145, 1.0, v145
	v_add_f32_e32 v146, 1.0, v146
	v_add_f32_e32 v147, 1.0, v147
	v_add_f32_e32 v142, 1.0, v142
	v_rcp_f32_e32 v145, v145
	v_rcp_f32_e32 v146, v146
	v_rcp_f32_e32 v147, v147
	v_rcp_f32_e32 v153, v142
	v_pk_mul_f32 v[122:123], v[122:123], v[144:145]
	v_pk_mul_f32 v[128:129], v[128:129], v[146:147]
	v_pk_mul_f32 v[124:125], v[124:125], v[152:153]

; #define PG8_STAGE(bufoff, gbase, voff) do { _Pragma("unroll") for (int _i = 0; _i < 2; ++_i) \
;         __builtin_amdgcn_global_load_lds((const unsigned*)((const char*)(gbase) + (voff)[_i]), (LAS unsigned*)(lds + (bufoff) + ldsw + _i * 8192), 16, 0, 0); } while (0)
; #define PG8_LDA(dst, b, h) do { _Pragma("unroll") for (int m = 0; m < 4; ++m) _Pragma("unroll") for (int k = 0; k < 2; ++k) dst[m][k] = *(const LAS f16x8*)(lds + PG8_SA(b, h) + aoff + m * 2048 + k * 1024); } while (0)
; #define PG8_LDB(dst, b, h) do { _Pragma("unroll") for (int n = 0; n < 2; ++n) _Pragma("unroll") for (int k = 0; k < 2; ++k) dst[n][k] = *(const LAS f16x8*)(lds + PG8_SB(b, h) + boff + n * 2048 + k * 1024); } while (0)
; #define PG8_MMA(ai, bj, At, Bt) do { __builtin_amdgcn_s_setprio(1); _Pragma("unroll") for (int m = 0; m < 4; ++m) _Pragma("unroll") for (int n = 0; n < 2; ++n) _Pragma("unroll") for (int k = 0; k < 2; ++k) \
;         acc[ai][bj][m][n] = __builtin_amdgcn_mfma_f32_16x16x32_f16(Bt[n][k], At[m][k], acc[ai][bj][m][n], 0, 0, 0); __builtin_amdgcn_s_setprio(0); } while (0)
; #define PG8_WAIT_V(n) asm volatile("s_waitcnt vmcnt(" #n ")" ::: "memory")
; #define PG8_WAIT_L(n) asm volatile("s_waitcnt lgkmcnt(" #n ")" ::: "memory")
; #define PG8_BAR __builtin_amdgcn_s_barrier()
; #define PG8_SCHED __builtin_amdgcn_sched_barrier(0)
; template <class Epi>
; __device__ __forceinline__ void gemm_phase(LAS unsigned char* lds, const Gemm g0, const StaticOrder& S, const Epi& E) {
;     ...
;             const char* a1 = cA + (size_t)(t + 1) * kstep;
;             const char* a2 = last ? nA : cA + (size_t)(t + 2) * kstep; const char* b2 = last ? nB : cB + (size_t)(t + 2) * kstep;
;             const char* a3 = a2 + kstep; const char* b3 = b2 + kstep;
;             PG8_LDB(B0, 0, 0); PG8_SCHED; PG8_LDA(At, 0, 0); PG8_STAGE(PG8_SA(1, 1), a1 + hstep, voffA);
;             PG8_WAIT_L(8); PG8_BAR; PG8_WAIT_L(0); PG8_MMA(0, 0, At, B0); PG8_BAR; PG8_SCHED;
;             PG8_LDB(B1, 0, 1); PG8_STAGE(PG8_SB(0, 0), b2, voffB);
;             PG8_BAR; PG8_WAIT_L(0); PG8_MMA(0, 1, At, B1); PG8_BAR;
;             PG8_LDA(At, 0, 1); PG8_STAGE(PG8_SA(0, 0), a2, voffA);
;             PG8_BAR; PG8_WAIT_L(0); PG8_MMA(1, 0, At, B0); PG8_BAR; PG8_SCHED;
;             PG8_STAGE(PG8_SB(0, 1), b2 + hstep, voffB);
;             PG8_WAIT_V(6); PG8_BAR; PG8_MMA(1, 1, At, B1); PG8_BAR;
.LBB0_620:
	s_add_u32 s58, s50, 0xfff80080
	s_addc_u32 s59, s51, -1
	s_and_b64 s[22:23], s[52:53], exec
	s_cselect_b32 s59, s37, s59
	s_cselect_b32 s58, s74, s58
	s_add_i32 s82, 0, 0x10000
	v_add_u32_e32 v68, s82, v189
	ds_read_b128 v[60:63], v68
	ds_read_b128 v[64:67], v68 offset:1024
	ds_read_b128 v[78:81], v68 offset:2048
	ds_read_b128 v[82:85], v68 offset:3072
	s_and_b64 s[22:23], s[52:53], exec
	s_cselect_b32 s53, s35, s25
	s_cselect_b32 s52, s75, s24
	s_add_i32 m0, s18, 0xc000
	ds_read_b128 v[86:89], v213
	ds_read_b128 v[90:93], v213 offset:1024
	ds_read_b128 v[194:197], v213 offset:2048
	ds_read_b128 v[234:237], v213 offset:3072
	ds_read_b128 v[238:241], v213 offset:4096
	ds_read_b128 v[242:245], v213 offset:5120
	ds_read_b128 v[246:249], v213 offset:6144
	ds_read_b128 v[226:229], v213 offset:7168
	global_load_lds_dwordx4 v184, s[50:51]
	s_add_i32 m0, s18, 0xe000
	s_nop 0
	global_load_lds_dwordx4 v182, s[50:51]
	s_waitcnt lgkmcnt(8)
	s_barrier
	s_waitcnt lgkmcnt(0)
	s_waitcnt lgkmcnt(0)
	v_mfma_f32_16x16x32_f16 v[158:161], v[60:63], v[86:89], v[158:161]
	v_mfma_f32_16x16x32_f16 v[150:153], v[78:81], v[86:89], v[150:153]
	v_mfma_f32_16x16x32_f16 v[142:145], v[60:63], v[194:197], v[142:145]
	v_mfma_f32_16x16x32_f16 v[134:137], v[78:81], v[194:197], v[134:137]
	v_mfma_f32_16x16x32_f16 v[126:129], v[60:63], v[238:241], v[126:129]
	v_mfma_f32_16x16x32_f16 v[118:121], v[78:81], v[238:241], v[118:121]
	v_mfma_f32_16x16x32_f16 v[110:113], v[60:63], v[246:249], v[110:113]
	v_mfma_f32_16x16x32_f16 v[102:105], v[78:81], v[246:249], v[102:105]
	v_mfma_f32_16x16x32_f16 v[158:161], v[64:67], v[90:93], v[158:161]
	v_mfma_f32_16x16x32_f16 v[150:153], v[82:85], v[90:93], v[150:153]
	v_mfma_f32_16x16x32_f16 v[142:145], v[64:67], v[234:237], v[142:145]
	v_mfma_f32_16x16x32_f16 v[134:137], v[82:85], v[234:237], v[134:137]
	v_mfma_f32_16x16x32_f16 v[126:129], v[64:67], v[242:245], v[126:129]
	v_mfma_f32_16x16x32_f16 v[118:121], v[82:85], v[242:245], v[118:121]
	v_mfma_f32_16x16x32_f16 v[110:113], v[64:67], v[226:229], v[110:113]
	v_mfma_f32_16x16x32_f16 v[102:105], v[82:85], v[226:229], v[102:105]
	s_barrier
	s_add_i32 s83, 0, 0x14000
	s_add_i32 s22, s82, s5
	v_add_u32_e32 v68, s83, v189
	v_add_u32_e32 v186, 0x80, v178
	s_mov_b32 m0, s22
	ds_read_b128 v[162:165], v68
	ds_read_b128 v[222:225], v68 offset:1024
	ds_read_b128 v[214:217], v68 offset:2048
	ds_read_b128 v[170:173], v68 offset:3072
	global_load_lds_dwordx4 v178, s[52:53]
	v_add_u32_e32 v190, 0x80, v174
	s_add_i32 m0, s22, 0x2000
	s_nop 0
	global_load_lds_dwordx4 v174, s[52:53]
	s_barrier
	s_waitcnt lgkmcnt(0)
	s_waitcnt lgkmcnt(0)
	v_mfma_f32_16x16x32_f16 v[154:157], v[162:165], v[86:89], v[154:157]
	v_mfma_f32_16x16x32_f16 v[86:89], v[214:217], v[86:89], v[146:149]
	v_mfma_f32_16x16x32_f16 v[130:133], v[214:217], v[194:197], v[130:133]
	v_mfma_f32_16x16x32_f16 v[122:125], v[162:165], v[238:241], v[122:125]
	v_mfma_f32_16x16x32_f16 v[114:117], v[214:217], v[238:241], v[114:117]
	v_mfma_f32_16x16x32_f16 v[106:109], v[162:165], v[246:249], v[106:109]
	v_mfma_f32_16x16x32_f16 v[98:101], v[214:217], v[246:249], v[98:101]
	v_mfma_f32_16x16x32_f16 v[154:157], v[222:225], v[90:93], v[154:157]
	v_mfma_f32_16x16x32_f16 v[86:89], v[170:173], v[90:93], v[86:89]
	v_mfma_f32_16x16x32_f16 v[90:93], v[162:165], v[194:197], v[138:141]
	v_mfma_f32_16x16x32_f16 v[130:133], v[170:173], v[234:237], v[130:133]
	v_mfma_f32_16x16x32_f16 v[122:125], v[222:225], v[242:245], v[122:125]
	v_mfma_f32_16x16x32_f16 v[114:117], v[170:173], v[242:245], v[114:117]
	v_mfma_f32_16x16x32_f16 v[106:109], v[222:225], v[226:229], v[106:109]
	v_mfma_f32_16x16x32_f16 v[98:101], v[170:173], v[226:229], v[98:101]
	v_mfma_f32_16x16x32_f16 v[90:93], v[222:225], v[234:237], v[90:93]
	s_mov_b32 m0, s18
	v_add_u32_e32 v198, 0x80, v180
	s_barrier
	ds_read_b128 v[138:141], v213 offset:16384
	ds_read_b128 v[146:149], v213 offset:17408
	ds_read_b128 v[194:197], v213 offset:18432
	ds_read_b128 v[226:229], v213 offset:19456
	ds_read_b128 v[234:237], v213 offset:20480
	ds_read_b128 v[238:241], v213 offset:21504
	ds_read_b128 v[242:245], v213 offset:22528
	ds_read_b128 v[246:249], v213 offset:23552
	global_load_lds_dwordx4 v180, s[58:59]
	v_add_u32_e32 v202, 0x80, v176
	s_mov_b32 m0, s19
	s_nop 0
	global_load_lds_dwordx4 v176, s[58:59]
	s_barrier
	s_waitcnt lgkmcnt(0)
	s_waitcnt lgkmcnt(0)
	v_mfma_f32_16x16x32_f16 v[94:97], v[60:63], v[138:141], v[94:97]
	v_mfma_f32_16x16x32_f16 v[68:71], v[78:81], v[138:141], v[70:73]
	v_mfma_f32_16x16x32_f16 v[46:49], v[60:63], v[194:197], v[46:49]
	v_mfma_f32_16x16x32_f16 v[38:41], v[78:81], v[194:197], v[38:41]
	v_mfma_f32_16x16x32_f16 v[30:33], v[60:63], v[234:237], v[30:33]
	v_mfma_f32_16x16x32_f16 v[22:25], v[78:81], v[234:237], v[22:25]
	v_mfma_f32_16x16x32_f16 v[14:17], v[60:63], v[242:245], v[14:17]
	v_mfma_f32_16x16x32_f16 v[6:9], v[78:81], v[242:245], v[6:9]
	v_mfma_f32_16x16x32_f16 v[94:97], v[64:67], v[146:149], v[94:97]
	v_mfma_f32_16x16x32_f16 v[68:71], v[82:85], v[146:149], v[68:71]
	v_mfma_f32_16x16x32_f16 v[46:49], v[64:67], v[226:229], v[46:49]
	v_mfma_f32_16x16x32_f16 v[38:41], v[82:85], v[226:229], v[38:41]
	v_mfma_f32_16x16x32_f16 v[30:33], v[64:67], v[238:241], v[30:33]
	v_mfma_f32_16x16x32_f16 v[22:25], v[82:85], v[238:241], v[22:25]
	v_mfma_f32_16x16x32_f16 v[14:17], v[64:67], v[246:249], v[14:17]
	v_mfma_f32_16x16x32_f16 v[6:9], v[82:85], v[246:249], v[6:9]
	s_barrier
	s_add_u32 s22, s52, 0x80000
	s_addc_u32 s23, s53, 0
	s_add_i32 s82, s83, s5
	s_mov_b32 m0, s82
	s_nop 0
	global_load_lds_dwordx4 v178, s[22:23]
	s_add_i32 m0, s82, 0x2000
	s_nop 0
	global_load_lds_dwordx4 v174, s[22:23]
	s_waitcnt vmcnt(6)
	s_barrier
; #define PG8_STAGE(bufoff, gbase, voff) do { _Pragma("unroll") for (int _i = 0; _i < 2; ++_i) \
;         __builtin_amdgcn_global_load_lds((const unsigned*)((const char*)(gbase) + (voff)[_i]), (LAS unsigned*)(lds + (bufoff) + ldsw + _i * 8192), 16, 0, 0); } while (0)
; #define PG8_LDA(dst, b, h) do { _Pragma("unroll") for (int m = 0; m < 4; ++m) _Pragma("unroll") for (int k = 0; k < 2; ++k) dst[m][k] = *(const LAS f16x8*)(lds + PG8_SA(b, h) + aoff + m * 2048 + k * 1024); } while (0)
; #define PG8_LDB(dst, b, h) do { _Pragma("unroll") for (int n = 0; n < 2; ++n) _Pragma("unroll") for (int k = 0; k < 2; ++k) dst[n][k] = *(const LAS f16x8*)(lds + PG8_SB(b, h) + boff + n * 2048 + k * 1024); } while (0)
; #define PG8_MMA(ai, bj, At, Bt) do { __builtin_amdgcn_s_setprio(1); _Pragma("unroll") for (int m = 0; m < 4; ++m) _Pragma("unroll") for (int n = 0; n < 2; ++n) _Pragma("unroll") for (int k = 0; k < 2; ++k) \
;         acc[ai][bj][m][n] = __builtin_amdgcn_mfma_f32_16x16x32_f16(Bt[n][k], At[m][k], acc[ai][bj][m][n], 0, 0, 0); __builtin_amdgcn_s_setprio(0); } while (0)
; #define PG8_WAIT_V(n) asm volatile("s_waitcnt vmcnt(" #n ")" ::: "memory")
; #define PG8_WAIT_L(n) asm volatile("s_waitcnt lgkmcnt(" #n ")" ::: "memory")
; #define PG8_BAR __builtin_amdgcn_s_barrier()
; #define PG8_SCHED __builtin_amdgcn_sched_barrier(0)
; template <class Epi>
; __device__ __forceinline__ void gemm_phase(LAS unsigned char* lds, const Gemm g0, const StaticOrder& S, const Epi& E) {
;     ...
;             PG8_WAIT_V(6); PG8_BAR; PG8_MMA(1, 1, At, B1); PG8_BAR;
;             PG8_LDB(B0, 1, 0); PG8_SCHED; PG8_LDA(At, 1, 0); PG8_STAGE(PG8_SA(0, 1), a2 + hstep, voffA);
;             PG8_WAIT_L(8); PG8_BAR; PG8_WAIT_L(0); PG8_MMA(0, 0, At, B0); PG8_BAR; PG8_SCHED;
;             PG8_LDB(B1, 1, 1); PG8_STAGE(PG8_SB(1, 0), b3, voffB);
;             PG8_BAR; PG8_WAIT_L(0); PG8_MMA(0, 1, At, B1); PG8_BAR;
	v_mfma_f32_16x16x32_f16 v[50:53], v[214:217], v[138:141], v[50:53]
	v_mfma_f32_16x16x32_f16 v[42:45], v[162:165], v[194:197], v[42:45]
	v_mfma_f32_16x16x32_f16 v[34:37], v[214:217], v[194:197], v[34:37]
	v_mfma_f32_16x16x32_f16 v[26:29], v[162:165], v[234:237], v[26:29]
	v_mfma_f32_16x16x32_f16 v[18:21], v[214:217], v[234:237], v[18:21]
	v_mfma_f32_16x16x32_f16 v[10:13], v[162:165], v[242:245], v[10:13]
	v_mfma_f32_16x16x32_f16 v[2:5], v[214:217], v[242:245], v[2:5]
	v_mfma_f32_16x16x32_f16 v[60:63], v[162:165], v[138:141], v[74:77]
	v_mfma_f32_16x16x32_f16 v[50:53], v[170:173], v[146:149], v[50:53]
	v_mfma_f32_16x16x32_f16 v[42:45], v[222:225], v[226:229], v[42:45]
	v_mfma_f32_16x16x32_f16 v[34:37], v[170:173], v[226:229], v[34:37]
	v_mfma_f32_16x16x32_f16 v[26:29], v[222:225], v[238:241], v[26:29]
	v_mfma_f32_16x16x32_f16 v[18:21], v[170:173], v[238:241], v[18:21]
	v_mfma_f32_16x16x32_f16 v[10:13], v[222:225], v[246:249], v[10:13]
	v_mfma_f32_16x16x32_f16 v[2:5], v[170:173], v[246:249], v[2:5]
	v_mfma_f32_16x16x32_f16 v[60:63], v[222:225], v[146:149], v[60:63]
	s_add_i32 s82, 0, 0x18000
	v_add_u32_e32 v72, s82, v189
	s_barrier
	ds_read_b128 v[64:67], v72
	ds_read_b128 v[74:77], v72 offset:1024
	ds_read_b128 v[78:81], v72 offset:2048
	ds_read_b128 v[82:85], v72 offset:3072
	s_add_u32 s22, s58, 0x80000
	s_addc_u32 s23, s59, 0
	s_mov_b32 m0, s28
	ds_read_b128 v[138:141], v213 offset:32768
	ds_read_b128 v[146:149], v213 offset:33792
	ds_read_b128 v[162:165], v213 offset:34816
	ds_read_b128 v[170:173], v213 offset:35840
	ds_read_b128 v[194:197], v213 offset:36864
	ds_read_b128 v[214:217], v213 offset:37888
	ds_read_b128 v[222:225], v213 offset:38912
	ds_read_b128 v[226:229], v213 offset:39936
	global_load_lds_dwordx4 v180, s[22:23]
	s_mov_b32 m0, s29
	s_nop 0
	global_load_lds_dwordx4 v176, s[22:23]
	s_waitcnt lgkmcnt(8)
	s_barrier
	s_waitcnt lgkmcnt(0)
	s_waitcnt lgkmcnt(0)
	v_mfma_f32_16x16x32_f16 v[158:161], v[64:67], v[138:141], v[158:161]
	v_mfma_f32_16x16x32_f16 v[150:153], v[78:81], v[138:141], v[150:153]
	v_mfma_f32_16x16x32_f16 v[142:145], v[64:67], v[162:165], v[142:145]
	v_mfma_f32_16x16x32_f16 v[134:137], v[78:81], v[162:165], v[134:137]
	v_mfma_f32_16x16x32_f16 v[126:129], v[64:67], v[194:197], v[126:129]
	v_mfma_f32_16x16x32_f16 v[118:121], v[78:81], v[194:197], v[118:121]
	v_mfma_f32_16x16x32_f16 v[110:113], v[64:67], v[222:225], v[110:113]
	v_mfma_f32_16x16x32_f16 v[102:105], v[78:81], v[222:225], v[102:105]
	v_mfma_f32_16x16x32_f16 v[158:161], v[74:77], v[146:149], v[158:161]
	v_mfma_f32_16x16x32_f16 v[150:153], v[82:85], v[146:149], v[150:153]
	v_mfma_f32_16x16x32_f16 v[142:145], v[74:77], v[170:173], v[142:145]
	v_mfma_f32_16x16x32_f16 v[134:137], v[82:85], v[170:173], v[134:137]
	v_mfma_f32_16x16x32_f16 v[126:129], v[74:77], v[214:217], v[126:129]
	v_mfma_f32_16x16x32_f16 v[118:121], v[82:85], v[214:217], v[118:121]
	v_mfma_f32_16x16x32_f16 v[110:113], v[74:77], v[226:229], v[110:113]
	v_mfma_f32_16x16x32_f16 v[102:105], v[82:85], v[226:229], v[102:105]
	s_barrier
	s_add_i32 s83, 0, 0x1c000
	v_add_u32_e32 v72, s83, v189
	s_add_i32 s22, s82, s5
	ds_read_b128 v[234:237], v72
	ds_read_b128 v[238:241], v72 offset:1024
	ds_read_b128 v[242:245], v72 offset:2048
	ds_read_b128 v[246:249], v72 offset:3072
	s_mov_b32 m0, s22
	s_nop 0
	global_load_lds_dwordx4 v186, s[52:53]
	s_add_i32 m0, s22, 0x2000
	s_nop 0
	global_load_lds_dwordx4 v190, s[52:53]
	s_barrier
; #define PG8_STAGE(bufoff, gbase, voff) do { _Pragma("unroll") for (int _i = 0; _i < 2; ++_i) \
;         __builtin_amdgcn_global_load_lds((const unsigned*)((const char*)(gbase) + (voff)[_i]), (LAS unsigned*)(lds + (bufoff) + ldsw + _i * 8192), 16, 0, 0); } while (0)
; #define PG8_LDA(dst, b, h) do { _Pragma("unroll") for (int m = 0; m < 4; ++m) _Pragma("unroll") for (int k = 0; k < 2; ++k) dst[m][k] = *(const LAS f16x8*)(lds + PG8_SA(b, h) + aoff + m * 2048 + k * 1024); } while (0)
; #define PG8_MMA(ai, bj, At, Bt) do { __builtin_amdgcn_s_setprio(1); _Pragma("unroll") for (int m = 0; m < 4; ++m) _Pragma("unroll") for (int n = 0; n < 2; ++n) _Pragma("unroll") for (int k = 0; k < 2; ++k) \
;         acc[ai][bj][m][n] = __builtin_amdgcn_mfma_f32_16x16x32_f16(Bt[n][k], At[m][k], acc[ai][bj][m][n], 0, 0, 0); __builtin_amdgcn_s_setprio(0); } while (0)
; #define PG8_WAIT_V(n) asm volatile("s_waitcnt vmcnt(" #n ")" ::: "memory")
; #define PG8_WAIT_L(n) asm volatile("s_waitcnt lgkmcnt(" #n ")" ::: "memory")
; #define PG8_BAR __builtin_amdgcn_s_barrier()
; #define PG8_SCHED __builtin_amdgcn_sched_barrier(0)
; template <class Epi>
; __device__ __forceinline__ void gemm_phase(LAS unsigned char* lds, const Gemm g0, const StaticOrder& S, const Epi& E) {
;     ...
;             PG8_BAR; PG8_WAIT_L(0); PG8_MMA(0, 1, At, B1); PG8_BAR;
;             PG8_LDA(At, 1, 1); PG8_STAGE(PG8_SA(1, 0), a3, voffA);
;             PG8_BAR; PG8_WAIT_L(0); PG8_MMA(1, 0, At, B0); PG8_BAR; PG8_SCHED;
;             PG8_STAGE(PG8_SB(1, 1), b3 + hstep, voffB);
;             PG8_WAIT_V(6); PG8_BAR; PG8_MMA(1, 1, At, B1); PG8_BAR;
;         }
	s_waitcnt lgkmcnt(0)
	s_waitcnt lgkmcnt(0)
	v_mfma_f32_16x16x32_f16 v[154:157], v[234:237], v[138:141], v[154:157]
	v_mfma_f32_16x16x32_f16 v[86:89], v[242:245], v[138:141], v[86:89]
	v_mfma_f32_16x16x32_f16 v[154:157], v[238:241], v[146:149], v[154:157]
	v_mfma_f32_16x16x32_f16 v[146:149], v[246:249], v[146:149], v[86:89]
	v_mfma_f32_16x16x32_f16 v[86:89], v[234:237], v[162:165], v[90:93]
	v_mfma_f32_16x16x32_f16 v[138:141], v[238:241], v[170:173], v[86:89]
	v_mfma_f32_16x16x32_f16 v[86:89], v[242:245], v[162:165], v[130:133]
	v_mfma_f32_16x16x32_f16 v[130:133], v[246:249], v[170:173], v[86:89]
	v_mfma_f32_16x16x32_f16 v[86:89], v[234:237], v[194:197], v[122:125]
	v_mfma_f32_16x16x32_f16 v[122:125], v[238:241], v[214:217], v[86:89]
	v_mfma_f32_16x16x32_f16 v[86:89], v[242:245], v[194:197], v[114:117]
	v_mfma_f32_16x16x32_f16 v[114:117], v[246:249], v[214:217], v[86:89]
	v_mfma_f32_16x16x32_f16 v[86:89], v[234:237], v[222:225], v[106:109]
	v_mfma_f32_16x16x32_f16 v[106:109], v[238:241], v[226:229], v[86:89]
	v_mfma_f32_16x16x32_f16 v[86:89], v[242:245], v[222:225], v[98:101]
	v_mfma_f32_16x16x32_f16 v[98:101], v[246:249], v[226:229], v[86:89]
	s_mov_b32 m0, s31
	s_barrier
	s_nop 2
	ds_read_b128 v[86:89], v213 offset:49152
	ds_read_b128 v[90:93], v213 offset:50176
	ds_read_b128 v[162:165], v213 offset:51200
	ds_read_b128 v[170:173], v213 offset:52224
	ds_read_b128 v[194:197], v213 offset:53248
	ds_read_b128 v[214:217], v213 offset:54272
	ds_read_b128 v[222:225], v213 offset:55296
	ds_read_b128 v[226:229], v213 offset:56320
	global_load_lds_dwordx4 v198, s[58:59]
	s_mov_b32 m0, s61
	s_nop 0
	global_load_lds_dwordx4 v202, s[58:59]
	s_barrier
	s_waitcnt lgkmcnt(0)
	s_waitcnt lgkmcnt(0)
	v_mfma_f32_16x16x32_f16 v[94:97], v[64:67], v[86:89], v[94:97]
	v_mfma_f32_16x16x32_f16 v[68:71], v[78:81], v[86:89], v[68:71]
	v_mfma_f32_16x16x32_f16 v[46:49], v[64:67], v[162:165], v[46:49]
	v_mfma_f32_16x16x32_f16 v[38:41], v[78:81], v[162:165], v[38:41]
	v_mfma_f32_16x16x32_f16 v[30:33], v[64:67], v[194:197], v[30:33]
	v_mfma_f32_16x16x32_f16 v[22:25], v[78:81], v[194:197], v[22:25]
	v_mfma_f32_16x16x32_f16 v[14:17], v[64:67], v[222:225], v[14:17]
	v_mfma_f32_16x16x32_f16 v[6:9], v[78:81], v[222:225], v[6:9]
	v_mfma_f32_16x16x32_f16 v[94:97], v[74:77], v[90:93], v[94:97]
	v_mfma_f32_16x16x32_f16 v[70:73], v[82:85], v[90:93], v[68:71]
	v_mfma_f32_16x16x32_f16 v[46:49], v[74:77], v[170:173], v[46:49]
	v_mfma_f32_16x16x32_f16 v[38:41], v[82:85], v[170:173], v[38:41]
	v_mfma_f32_16x16x32_f16 v[30:33], v[74:77], v[214:217], v[30:33]
	v_mfma_f32_16x16x32_f16 v[22:25], v[82:85], v[214:217], v[22:25]
	v_mfma_f32_16x16x32_f16 v[14:17], v[74:77], v[226:229], v[14:17]
	v_mfma_f32_16x16x32_f16 v[6:9], v[82:85], v[226:229], v[6:9]
	s_barrier
	s_add_u32 s22, s52, 0x80080
	s_addc_u32 s23, s53, 0
	s_add_i32 s52, s83, s5
	s_mov_b32 m0, s52
	s_nop 0
	global_load_lds_dwordx4 v178, s[22:23]
	v_lshl_add_u64 v[64:65], s[22:23], 0, v[174:175]
	s_add_i32 m0, s52, 0x2000
	s_nop 0
	global_load_lds_dwordx4 v[64:65], off
	s_waitcnt vmcnt(6)
	s_barrier
	v_mfma_f32_16x16x32_f16 v[60:63], v[234:237], v[86:89], v[60:63]
	v_mfma_f32_16x16x32_f16 v[50:53], v[242:245], v[86:89], v[50:53]
	v_mfma_f32_16x16x32_f16 v[42:45], v[234:237], v[162:165], v[42:45]
	v_mfma_f32_16x16x32_f16 v[34:37], v[242:245], v[162:165], v[34:37]
	v_mfma_f32_16x16x32_f16 v[26:29], v[234:237], v[194:197], v[26:29]
	v_mfma_f32_16x16x32_f16 v[18:21], v[242:245], v[194:197], v[18:21]
	v_mfma_f32_16x16x32_f16 v[10:13], v[234:237], v[222:225], v[10:13]
	v_mfma_f32_16x16x32_f16 v[2:5], v[242:245], v[222:225], v[2:5]
	v_mfma_f32_16x16x32_f16 v[74:77], v[238:241], v[90:93], v[60:63]
	v_mfma_f32_16x16x32_f16 v[50:53], v[246:249], v[90:93], v[50:53]
	v_mfma_f32_16x16x32_f16 v[42:45], v[238:241], v[170:173], v[42:45]
	v_mfma_f32_16x16x32_f16 v[34:37], v[246:249], v[170:173], v[34:37]
	v_mfma_f32_16x16x32_f16 v[26:29], v[238:241], v[214:217], v[26:29]
	v_mfma_f32_16x16x32_f16 v[18:21], v[246:249], v[214:217], v[18:21]
	v_mfma_f32_16x16x32_f16 v[10:13], v[238:241], v[226:229], v[10:13]
	v_mfma_f32_16x16x32_f16 v[2:5], v[246:249], v[226:229], v[2:5]
	s_add_i32 s81, s81, 2
	s_add_u32 s24, s24, 0x100
	s_addc_u32 s25, s25, 0
	s_add_u32 s50, s50, 0x100
	s_addc_u32 s51, s51, 0
	s_cmp_gt_u32 s81, 29
	s_barrier
	s_cbranch_scc1 .LBB0_616

;     __device__ __forceinline__ void prefetch(const Unit& u, int wr, int wc, int lane) const { lnfold_prefetch(vl, stats, gW, bW, u, wr, wc, lane); }
;     __device__ __forceinline__ void prefetch(const Unit& u, int wr, int wc, int lane) const { lnfold_prefetch(vl, stats, gW, bW, u, wr, wc, lane); }
; #define PG8_STAGE(bufoff, gbase, voff) do { _Pragma("unroll") for (int _i = 0; _i < 2; ++_i) \
;         __builtin_amdgcn_global_load_lds((const unsigned*)((const char*)(gbase) + (voff)[_i]), (LAS unsigned*)(lds + (bufoff) + ldsw + _i * 8192), 16, 0, 0); } while (0)
; #define PG8_LDA(dst, b, h) do { _Pragma("unroll") for (int m = 0; m < 4; ++m) _Pragma("unroll") for (int k = 0; k < 2; ++k) dst[m][k] = *(const LAS f16x8*)(lds + PG8_SA(b, h) + aoff + m * 2048 + k * 1024); } while (0)
; #define PG8_LDB(dst, b, h) do { _Pragma("unroll") for (int n = 0; n < 2; ++n) _Pragma("unroll") for (int k = 0; k < 2; ++k) dst[n][k] = *(const LAS f16x8*)(lds + PG8_SB(b, h) + boff + n * 2048 + k * 1024); } while (0)
; #define PG8_WAIT_V(n) asm volatile("s_waitcnt vmcnt(" #n ")" ::: "memory")
; #define PG8_WAIT_L(n) asm volatile("s_waitcnt lgkmcnt(" #n ")" ::: "memory")
; #define PG8_BAR __builtin_amdgcn_s_barrier()
; template <class Epi>
; __device__ __forceinline__ void gemm_phase(LAS unsigned char* lds, const Gemm g0, const StaticOrder& S, const Epi& E) {
;     ...
;             const bool last = (t == nt - 2);
;             if (Epi::PREF && last) E.prefetch(cur, wr, wc, lane);
;             const char* a1 = cA + (size_t)(t + 1) * kstep;
;             const char* a2 = last ? nA : cA + (size_t)(t + 2) * kstep; const char* b2 = last ? nB : cB + (size_t)(t + 2) * kstep;
;             const char* a3 = a2 + kstep; const char* b3 = b2 + kstep;
;             PG8_LDB(B0, 0, 0); PG8_SCHED; PG8_LDA(At, 0, 0); PG8_STAGE(PG8_SA(1, 1), a1 + hstep, voffA);
;             PG8_WAIT_L(8); PG8_BAR; PG8_WAIT_L(0); PG8_MMA(0, 0, At, B0); PG8_BAR; PG8_SCHED;
;             PG8_LDB(B1, 0, 1); PG8_STAGE(PG8_SB(0, 0), b2, voffB);
;             PG8_BAR; PG8_WAIT_L(0); PG8_MMA(0, 1, At, B1); PG8_BAR;
;             PG8_LDA(At, 0, 1); PG8_STAGE(PG8_SA(0, 0), a2, voffA);
;             PG8_BAR; PG8_WAIT_L(0); PG8_MMA(1, 0, At, B0); PG8_BAR; PG8_SCHED;
;             PG8_STAGE(PG8_SB(0, 1), b2 + hstep, voffB);
;             PG8_WAIT_V(6); PG8_BAR; PG8_MMA(1, 1, At, B1); PG8_BAR;
.LBB0_672:
	s_add_u32 s10, s12, 0x100
	s_addc_u32 s11, s13, 0
	s_add_i32 s23, 0, 0x10000
	v_add_u32_e32 v142, s23, v203
	ds_read_b128 v[130:133], v142
	ds_read_b128 v[134:137], v142 offset:1024
	ds_read_b128 v[138:141], v142 offset:2048
	ds_read_b128 v[142:145], v142 offset:3072
	s_cmpk_eq_i32 s22, 0x54
	s_cselect_b32 s81, s1, s11
	s_cselect_b32 s80, s0, s10
	s_cselect_b32 s63, s59, s25
	s_cselect_b32 s62, s58, s24
	s_add_i32 m0, s28, 0xc000
	ds_read_b128 v[146:149], v208
	ds_read_b128 v[150:153], v208 offset:1024
	ds_read_b128 v[154:157], v208 offset:2048
	ds_read_b128 v[162:165], v208 offset:3072
	ds_read_b128 v[170:173], v208 offset:4096
	ds_read_b128 v[184:187], v208 offset:5120
	ds_read_b128 v[188:191], v208 offset:6144
	ds_read_b128 v[192:195], v208 offset:7168
	global_load_lds_dwordx4 v182, s[12:13]
	s_add_i32 m0, s28, 0xe000
	s_nop 0
	global_load_lds_dwordx4 v180, s[12:13]
	s_waitcnt lgkmcnt(8)
	s_barrier
	s_waitcnt lgkmcnt(0)
	s_waitcnt lgkmcnt(0)
	v_mfma_f32_16x16x32_f16 v[126:129], v[130:133], v[146:149], v[126:129]
	v_mfma_f32_16x16x32_f16 v[122:125], v[138:141], v[146:149], v[122:125]
	v_mfma_f32_16x16x32_f16 v[110:113], v[130:133], v[154:157], v[110:113]
	v_mfma_f32_16x16x32_f16 v[106:109], v[138:141], v[154:157], v[106:109]
	v_mfma_f32_16x16x32_f16 v[94:97], v[130:133], v[170:173], v[94:97]
	v_mfma_f32_16x16x32_f16 v[90:93], v[138:141], v[170:173], v[90:93]
	v_mfma_f32_16x16x32_f16 v[78:81], v[130:133], v[188:191], v[78:81]
	v_mfma_f32_16x16x32_f16 v[74:77], v[138:141], v[188:191], v[74:77]
	v_mfma_f32_16x16x32_f16 v[126:129], v[134:137], v[150:153], v[126:129]
	v_mfma_f32_16x16x32_f16 v[122:125], v[142:145], v[150:153], v[122:125]
	v_mfma_f32_16x16x32_f16 v[110:113], v[134:137], v[162:165], v[110:113]
	v_mfma_f32_16x16x32_f16 v[106:109], v[142:145], v[162:165], v[106:109]
	v_mfma_f32_16x16x32_f16 v[94:97], v[134:137], v[184:187], v[94:97]
	v_mfma_f32_16x16x32_f16 v[90:93], v[142:145], v[184:187], v[90:93]
	v_mfma_f32_16x16x32_f16 v[78:81], v[134:137], v[192:195], v[78:81]
	v_mfma_f32_16x16x32_f16 v[74:77], v[142:145], v[192:195], v[74:77]
	s_barrier
	s_add_i32 s90, 0, 0x14000
	v_add_u32_e32 v200, s90, v203
	s_add_i32 s12, s23, s19
	ds_read_b128 v[196:199], v200
	ds_read_b128 v[210:213], v200 offset:1024
	ds_read_b128 v[214:217], v200 offset:2048
	ds_read_b128 v[222:225], v200 offset:3072
	v_add_u32_e32 v200, 0x80, v174
	s_mov_b32 m0, s12
	v_add_u32_e32 v218, 0x80, v158
	global_load_lds_dwordx4 v174, s[62:63]
	s_add_i32 m0, s12, 0x2000
	s_nop 0
	global_load_lds_dwordx4 v158, s[62:63]
	s_barrier
	s_waitcnt lgkmcnt(0)
	s_waitcnt lgkmcnt(0)
	v_mfma_f32_16x16x32_f16 v[118:121], v[196:199], v[146:149], v[118:121]
	v_mfma_f32_16x16x32_f16 v[114:117], v[214:217], v[146:149], v[114:117]
	v_mfma_f32_16x16x32_f16 v[102:105], v[196:199], v[154:157], v[102:105]
	v_mfma_f32_16x16x32_f16 v[98:101], v[214:217], v[154:157], v[98:101]
	v_mfma_f32_16x16x32_f16 v[86:89], v[196:199], v[170:173], v[86:89]
	v_mfma_f32_16x16x32_f16 v[82:85], v[214:217], v[170:173], v[82:85]
	v_mfma_f32_16x16x32_f16 v[70:73], v[196:199], v[188:191], v[70:73]
	v_mfma_f32_16x16x32_f16 v[66:69], v[214:217], v[188:191], v[66:69]
	v_mfma_f32_16x16x32_f16 v[118:121], v[210:213], v[150:153], v[118:121]
	v_mfma_f32_16x16x32_f16 v[114:117], v[222:225], v[150:153], v[114:117]
	v_mfma_f32_16x16x32_f16 v[102:105], v[210:213], v[162:165], v[102:105]
	v_mfma_f32_16x16x32_f16 v[98:101], v[222:225], v[162:165], v[98:101]
	v_mfma_f32_16x16x32_f16 v[86:89], v[210:213], v[184:187], v[86:89]
	v_mfma_f32_16x16x32_f16 v[82:85], v[222:225], v[184:187], v[82:85]
	v_mfma_f32_16x16x32_f16 v[70:73], v[210:213], v[192:195], v[70:73]
	v_mfma_f32_16x16x32_f16 v[66:69], v[222:225], v[192:195], v[66:69]
	s_mov_b32 m0, s28
	v_add_u32_e32 v226, 0x80, v176
	s_barrier
	ds_read_b128 v[146:149], v208 offset:16384
	ds_read_b128 v[150:153], v208 offset:17408
	ds_read_b128 v[154:157], v208 offset:18432
	ds_read_b128 v[162:165], v208 offset:19456
	ds_read_b128 v[170:173], v208 offset:20480
	ds_read_b128 v[184:187], v208 offset:21504
	ds_read_b128 v[188:191], v208 offset:22528
	ds_read_b128 v[192:195], v208 offset:23552
	global_load_lds_dwordx4 v176, s[80:81]
	v_add_u32_e32 v228, 0x80, v160
	s_mov_b32 m0, s29
	s_nop 0
	global_load_lds_dwordx4 v160, s[80:81]
	s_barrier
	s_waitcnt lgkmcnt(0)
	s_waitcnt lgkmcnt(0)
	v_mfma_f32_16x16x32_f16 v[62:65], v[130:133], v[146:149], v[62:65]
	v_mfma_f32_16x16x32_f16 v[58:61], v[138:141], v[146:149], v[58:61]
	v_mfma_f32_16x16x32_f16 v[46:49], v[130:133], v[154:157], v[46:49]
	v_mfma_f32_16x16x32_f16 v[42:45], v[138:141], v[154:157], v[42:45]
	v_mfma_f32_16x16x32_f16 v[30:33], v[130:133], v[170:173], v[30:33]
	v_mfma_f32_16x16x32_f16 v[26:29], v[138:141], v[170:173], v[26:29]
	v_mfma_f32_16x16x32_f16 v[14:17], v[130:133], v[188:191], v[14:17]
	v_mfma_f32_16x16x32_f16 v[10:13], v[138:141], v[188:191], v[10:13]
	v_mfma_f32_16x16x32_f16 v[62:65], v[134:137], v[150:153], v[62:65]
	v_mfma_f32_16x16x32_f16 v[58:61], v[142:145], v[150:153], v[58:61]
	v_mfma_f32_16x16x32_f16 v[46:49], v[134:137], v[162:165], v[46:49]
	v_mfma_f32_16x16x32_f16 v[42:45], v[142:145], v[162:165], v[42:45]
	v_mfma_f32_16x16x32_f16 v[30:33], v[134:137], v[184:187], v[30:33]
	v_mfma_f32_16x16x32_f16 v[26:29], v[142:145], v[184:187], v[26:29]
	v_mfma_f32_16x16x32_f16 v[14:17], v[134:137], v[192:195], v[14:17]
	v_mfma_f32_16x16x32_f16 v[10:13], v[142:145], v[192:195], v[10:13]
	s_barrier
	s_add_u32 s12, s62, 0x160000
	s_addc_u32 s13, s63, 0
	s_add_i32 s23, s90, s19
	s_mov_b32 m0, s23
	s_nop 0
	global_load_lds_dwordx4 v174, s[12:13]
	s_add_i32 m0, s23, 0x2000
	s_nop 0
	global_load_lds_dwordx4 v158, s[12:13]
	s_waitcnt vmcnt(6)
	s_barrier
; #define PG8_STAGE(bufoff, gbase, voff) do { _Pragma("unroll") for (int _i = 0; _i < 2; ++_i) \
;         __builtin_amdgcn_global_load_lds((const unsigned*)((const char*)(gbase) + (voff)[_i]), (LAS unsigned*)(lds + (bufoff) + ldsw + _i * 8192), 16, 0, 0); } while (0)
; #define PG8_LDA(dst, b, h) do { _Pragma("unroll") for (int m = 0; m < 4; ++m) _Pragma("unroll") for (int k = 0; k < 2; ++k) dst[m][k] = *(const LAS f16x8*)(lds + PG8_SA(b, h) + aoff + m * 2048 + k * 1024); } while (0)
; #define PG8_LDB(dst, b, h) do { _Pragma("unroll") for (int n = 0; n < 2; ++n) _Pragma("unroll") for (int k = 0; k < 2; ++k) dst[n][k] = *(const LAS f16x8*)(lds + PG8_SB(b, h) + boff + n * 2048 + k * 1024); } while (0)
; #define PG8_MMA(ai, bj, At, Bt) do { __builtin_amdgcn_s_setprio(1); _Pragma("unroll") for (int m = 0; m < 4; ++m) _Pragma("unroll") for (int n = 0; n < 2; ++n) _Pragma("unroll") for (int k = 0; k < 2; ++k) \
;         acc[ai][bj][m][n] = __builtin_amdgcn_mfma_f32_16x16x32_f16(Bt[n][k], At[m][k], acc[ai][bj][m][n], 0, 0, 0); __builtin_amdgcn_s_setprio(0); } while (0)
; #define PG8_WAIT_V(n) asm volatile("s_waitcnt vmcnt(" #n ")" ::: "memory")
; #define PG8_WAIT_L(n) asm volatile("s_waitcnt lgkmcnt(" #n ")" ::: "memory")
; #define PG8_BAR __builtin_amdgcn_s_barrier()
; #define PG8_SCHED __builtin_amdgcn_sched_barrier(0)
; template <class Epi>
; __device__ __forceinline__ void gemm_phase(LAS unsigned char* lds, const Gemm g0, const StaticOrder& S, const Epi& E) {
;     ...
;             PG8_WAIT_V(6); PG8_BAR; PG8_MMA(1, 1, At, B1); PG8_BAR;
;             PG8_LDB(B0, 1, 0); PG8_SCHED; PG8_LDA(At, 1, 0); PG8_STAGE(PG8_SA(0, 1), a2 + hstep, voffA);
;             PG8_WAIT_L(8); PG8_BAR; PG8_WAIT_L(0); PG8_MMA(0, 0, At, B0); PG8_BAR; PG8_SCHED;
;             PG8_LDB(B1, 1, 1); PG8_STAGE(PG8_SB(1, 0), b3, voffB);
;             PG8_BAR; PG8_WAIT_L(0); PG8_MMA(0, 1, At, B1); PG8_BAR;
	v_mfma_f32_16x16x32_f16 v[54:57], v[196:199], v[146:149], v[54:57]
	v_mfma_f32_16x16x32_f16 v[50:53], v[214:217], v[146:149], v[50:53]
	v_mfma_f32_16x16x32_f16 v[38:41], v[196:199], v[154:157], v[38:41]
	v_mfma_f32_16x16x32_f16 v[34:37], v[214:217], v[154:157], v[34:37]
	v_mfma_f32_16x16x32_f16 v[22:25], v[196:199], v[170:173], v[22:25]
	v_mfma_f32_16x16x32_f16 v[18:21], v[214:217], v[170:173], v[18:21]
	v_mfma_f32_16x16x32_f16 v[6:9], v[196:199], v[188:191], v[6:9]
	v_mfma_f32_16x16x32_f16 v[2:5], v[214:217], v[188:191], v[2:5]
	v_mfma_f32_16x16x32_f16 v[54:57], v[210:213], v[150:153], v[54:57]
	v_mfma_f32_16x16x32_f16 v[50:53], v[222:225], v[150:153], v[50:53]
	v_mfma_f32_16x16x32_f16 v[38:41], v[210:213], v[162:165], v[38:41]
	v_mfma_f32_16x16x32_f16 v[34:37], v[222:225], v[162:165], v[34:37]
	v_mfma_f32_16x16x32_f16 v[22:25], v[210:213], v[184:187], v[22:25]
	v_mfma_f32_16x16x32_f16 v[18:21], v[222:225], v[184:187], v[18:21]
	v_mfma_f32_16x16x32_f16 v[6:9], v[210:213], v[192:195], v[6:9]
	v_mfma_f32_16x16x32_f16 v[2:5], v[222:225], v[192:195], v[2:5]
	s_add_i32 s23, 0, 0x18000
	v_add_u32_e32 v142, s23, v203
	s_barrier
	ds_read_b128 v[130:133], v142
	ds_read_b128 v[134:137], v142 offset:1024
	ds_read_b128 v[138:141], v142 offset:2048
	ds_read_b128 v[142:145], v142 offset:3072
	s_add_u32 s12, s80, 0x160000
	s_addc_u32 s13, s81, 0
	s_mov_b32 m0, s31
	ds_read_b128 v[146:149], v208 offset:32768
	ds_read_b128 v[150:153], v208 offset:33792
	ds_read_b128 v[154:157], v208 offset:34816
	ds_read_b128 v[162:165], v208 offset:35840
	ds_read_b128 v[170:173], v208 offset:36864
	ds_read_b128 v[184:187], v208 offset:37888
	ds_read_b128 v[188:191], v208 offset:38912
	ds_read_b128 v[192:195], v208 offset:39936
	global_load_lds_dwordx4 v176, s[12:13]
	s_mov_b32 m0, s61
	s_nop 0
	global_load_lds_dwordx4 v160, s[12:13]
	s_waitcnt lgkmcnt(8)
	s_barrier
	s_waitcnt lgkmcnt(0)
	s_waitcnt lgkmcnt(0)
	v_mfma_f32_16x16x32_f16 v[126:129], v[130:133], v[146:149], v[126:129]
	v_mfma_f32_16x16x32_f16 v[122:125], v[138:141], v[146:149], v[122:125]
	v_mfma_f32_16x16x32_f16 v[110:113], v[130:133], v[154:157], v[110:113]
	v_mfma_f32_16x16x32_f16 v[106:109], v[138:141], v[154:157], v[106:109]
	v_mfma_f32_16x16x32_f16 v[94:97], v[130:133], v[170:173], v[94:97]
	v_mfma_f32_16x16x32_f16 v[90:93], v[138:141], v[170:173], v[90:93]
	v_mfma_f32_16x16x32_f16 v[78:81], v[130:133], v[188:191], v[78:81]
	v_mfma_f32_16x16x32_f16 v[74:77], v[138:141], v[188:191], v[74:77]
	v_mfma_f32_16x16x32_f16 v[126:129], v[134:137], v[150:153], v[126:129]
	v_mfma_f32_16x16x32_f16 v[122:125], v[142:145], v[150:153], v[122:125]
	v_mfma_f32_16x16x32_f16 v[110:113], v[134:137], v[162:165], v[110:113]
	v_mfma_f32_16x16x32_f16 v[106:109], v[142:145], v[162:165], v[106:109]
	v_mfma_f32_16x16x32_f16 v[94:97], v[134:137], v[184:187], v[94:97]
	v_mfma_f32_16x16x32_f16 v[90:93], v[142:145], v[184:187], v[90:93]
	v_mfma_f32_16x16x32_f16 v[78:81], v[134:137], v[192:195], v[78:81]
	v_mfma_f32_16x16x32_f16 v[74:77], v[142:145], v[192:195], v[74:77]
	s_barrier
	s_add_i32 s90, 0, 0x1c000
	s_add_i32 s12, s23, s19
	v_add_u32_e32 v209, s90, v203
	s_mov_b32 m0, s12
	ds_read_b128 v[196:199], v209
	ds_read_b128 v[210:213], v209 offset:1024
	ds_read_b128 v[214:217], v209 offset:2048
	ds_read_b128 v[222:225], v209 offset:3072
	global_load_lds_dwordx4 v200, s[62:63]
	s_add_i32 m0, s12, 0x2000
	s_nop 0
	global_load_lds_dwordx4 v218, s[62:63]
	s_barrier
	s_waitcnt lgkmcnt(0)
	s_waitcnt lgkmcnt(0)
	v_mfma_f32_16x16x32_f16 v[118:121], v[196:199], v[146:149], v[118:121]
	v_mfma_f32_16x16x32_f16 v[114:117], v[214:217], v[146:149], v[114:117]
	v_mfma_f32_16x16x32_f16 v[102:105], v[196:199], v[154:157], v[102:105]
	v_mfma_f32_16x16x32_f16 v[98:101], v[214:217], v[154:157], v[98:101]
	v_mfma_f32_16x16x32_f16 v[86:89], v[196:199], v[170:173], v[86:89]
	v_mfma_f32_16x16x32_f16 v[82:85], v[214:217], v[170:173], v[82:85]
	v_mfma_f32_16x16x32_f16 v[70:73], v[196:199], v[188:191], v[70:73]
	v_mfma_f32_16x16x32_f16 v[66:69], v[214:217], v[188:191], v[66:69]
	v_mfma_f32_16x16x32_f16 v[118:121], v[210:213], v[150:153], v[118:121]
	v_mfma_f32_16x16x32_f16 v[114:117], v[222:225], v[150:153], v[114:117]
	v_mfma_f32_16x16x32_f16 v[102:105], v[210:213], v[162:165], v[102:105]
	v_mfma_f32_16x16x32_f16 v[98:101], v[222:225], v[162:165], v[98:101]
	v_mfma_f32_16x16x32_f16 v[86:89], v[210:213], v[184:187], v[86:89]
	v_mfma_f32_16x16x32_f16 v[82:85], v[222:225], v[184:187], v[82:85]
	v_mfma_f32_16x16x32_f16 v[70:73], v[210:213], v[192:195], v[70:73]
	v_mfma_f32_16x16x32_f16 v[66:69], v[222:225], v[192:195], v[66:69]
	s_mov_b32 m0, s83
	s_barrier
; #define GAS __attribute__((address_space(1)))
; #define PG8_STAGE(bufoff, gbase, voff) do { _Pragma("unroll") for (int _i = 0; _i < 2; ++_i) \
;         __builtin_amdgcn_global_load_lds((const unsigned*)((const char*)(gbase) + (voff)[_i]), (LAS unsigned*)(lds + (bufoff) + ldsw + _i * 8192), 16, 0, 0); } while (0)
; #define PG8_LDA(dst, b, h) do { _Pragma("unroll") for (int m = 0; m < 4; ++m) _Pragma("unroll") for (int k = 0; k < 2; ++k) dst[m][k] = *(const LAS f16x8*)(lds + PG8_SA(b, h) + aoff + m * 2048 + k * 1024); } while (0)
; #define PG8_MMA(ai, bj, At, Bt) do { __builtin_amdgcn_s_setprio(1); _Pragma("unroll") for (int m = 0; m < 4; ++m) _Pragma("unroll") for (int n = 0; n < 2; ++n) _Pragma("unroll") for (int k = 0; k < 2; ++k) \
;         acc[ai][bj][m][n] = __builtin_amdgcn_mfma_f32_16x16x32_f16(Bt[n][k], At[m][k], acc[ai][bj][m][n], 0, 0, 0); __builtin_amdgcn_s_setprio(0); } while (0)
; #define PG8_WAIT_V(n) asm volatile("s_waitcnt vmcnt(" #n ")" ::: "memory")
; #define PG8_WAIT_L(n) asm volatile("s_waitcnt lgkmcnt(" #n ")" ::: "memory")
; #define PG8_BAR __builtin_amdgcn_s_barrier()
; #define PG8_SCHED __builtin_amdgcn_sched_barrier(0)
;     __device__ __forceinline__ void operator()(f32x4 (&acc)[2][2][4][2], const Unit& u, int wr, int wc, int fr, int fq) const {
;     ...
;         { const int lane = fr + 16 * fq, cL = u.pn * BM + wc * 32 + (lane < 32 ? lane : 96 + lane);
;           float vg = 0.f, vb = 0.f, vt = 0.f;
;           if (hasln) { vg = *(const GAS float*)(pg + cL); vb = *(const GAS float*)(pb + cL); }
;           if (haszh) vt = *(const GAS float*)(tg + cL);
; template <class Epi>
; __device__ __forceinline__ void gemm_phase(LAS unsigned char* lds, const Gemm g0, const StaticOrder& S, const Epi& E) {
;     ...
;             PG8_LDA(At, 1, 1); PG8_STAGE(PG8_SA(1, 0), a3, voffA);
;             PG8_BAR; PG8_WAIT_L(0); PG8_MMA(1, 0, At, B0); PG8_BAR; PG8_SCHED;
;             PG8_STAGE(PG8_SB(1, 1), b3 + hstep, voffB);
;             PG8_WAIT_V(6); PG8_BAR; PG8_MMA(1, 1, At, B1); PG8_BAR;
;         }
	ds_read_b128 v[146:149], v208 offset:49152
	ds_read_b128 v[150:153], v208 offset:50176
	ds_read_b128 v[154:157], v208 offset:51200
	ds_read_b128 v[162:165], v208 offset:52224
	ds_read_b128 v[170:173], v208 offset:53248
	ds_read_b128 v[184:187], v208 offset:54272
	ds_read_b128 v[188:191], v208 offset:55296
	ds_read_b128 v[192:195], v208 offset:56320
	global_load_lds_dwordx4 v226, s[80:81]
	s_mov_b32 m0, s84
	s_nop 0
	global_load_lds_dwordx4 v228, s[80:81]
	s_barrier
	s_waitcnt lgkmcnt(0)
	s_waitcnt lgkmcnt(0)
	v_mfma_f32_16x16x32_f16 v[62:65], v[130:133], v[146:149], v[62:65]
	v_mfma_f32_16x16x32_f16 v[58:61], v[138:141], v[146:149], v[58:61]
	v_mfma_f32_16x16x32_f16 v[46:49], v[130:133], v[154:157], v[46:49]
	v_mfma_f32_16x16x32_f16 v[42:45], v[138:141], v[154:157], v[42:45]
	v_mfma_f32_16x16x32_f16 v[30:33], v[130:133], v[170:173], v[30:33]
	v_mfma_f32_16x16x32_f16 v[26:29], v[138:141], v[170:173], v[26:29]
	v_mfma_f32_16x16x32_f16 v[14:17], v[130:133], v[188:191], v[14:17]
	v_mfma_f32_16x16x32_f16 v[10:13], v[138:141], v[188:191], v[10:13]
	v_mfma_f32_16x16x32_f16 v[62:65], v[134:137], v[150:153], v[62:65]
	v_mfma_f32_16x16x32_f16 v[58:61], v[142:145], v[150:153], v[58:61]
	v_mfma_f32_16x16x32_f16 v[46:49], v[134:137], v[162:165], v[46:49]
	v_mfma_f32_16x16x32_f16 v[42:45], v[142:145], v[162:165], v[42:45]
	v_mfma_f32_16x16x32_f16 v[30:33], v[134:137], v[184:187], v[30:33]
	v_mfma_f32_16x16x32_f16 v[26:29], v[142:145], v[184:187], v[26:29]
	v_mfma_f32_16x16x32_f16 v[14:17], v[134:137], v[192:195], v[14:17]
	v_mfma_f32_16x16x32_f16 v[10:13], v[142:145], v[192:195], v[10:13]
	s_barrier
	s_add_u32 s12, s62, 0x160080
	s_addc_u32 s13, s63, 0
	s_add_i32 s23, s90, s19
	s_mov_b32 m0, s23
	s_nop 0
	global_load_lds_dwordx4 v174, s[12:13]
	s_add_i32 m0, s23, 0x2000
	s_nop 0
	global_load_lds_dwordx4 v158, s[12:13]
	s_waitcnt vmcnt(6)
	s_barrier
	v_mfma_f32_16x16x32_f16 v[54:57], v[196:199], v[146:149], v[54:57]
	v_mfma_f32_16x16x32_f16 v[50:53], v[214:217], v[146:149], v[50:53]
	v_mfma_f32_16x16x32_f16 v[38:41], v[196:199], v[154:157], v[38:41]
	v_mfma_f32_16x16x32_f16 v[34:37], v[214:217], v[154:157], v[34:37]
	v_mfma_f32_16x16x32_f16 v[22:25], v[196:199], v[170:173], v[22:25]
	v_mfma_f32_16x16x32_f16 v[18:21], v[214:217], v[170:173], v[18:21]
	v_mfma_f32_16x16x32_f16 v[6:9], v[196:199], v[188:191], v[6:9]
	v_mfma_f32_16x16x32_f16 v[2:5], v[214:217], v[188:191], v[2:5]
	v_mfma_f32_16x16x32_f16 v[54:57], v[210:213], v[150:153], v[54:57]
	v_mfma_f32_16x16x32_f16 v[50:53], v[222:225], v[150:153], v[50:53]
	v_mfma_f32_16x16x32_f16 v[38:41], v[210:213], v[162:165], v[38:41]
	v_mfma_f32_16x16x32_f16 v[34:37], v[222:225], v[162:165], v[34:37]
	v_mfma_f32_16x16x32_f16 v[22:25], v[210:213], v[184:187], v[22:25]
	v_mfma_f32_16x16x32_f16 v[18:21], v[222:225], v[184:187], v[18:21]
	v_mfma_f32_16x16x32_f16 v[6:9], v[210:213], v[192:195], v[6:9]
	v_mfma_f32_16x16x32_f16 v[2:5], v[222:225], v[192:195], v[2:5]
	s_add_i32 s22, s22, 2
	s_add_u32 s24, s24, 0x100
	s_addc_u32 s25, s25, 0
	s_cmpk_gt_u32 s22, 0x55
	s_mov_b64 s[12:13], s[10:11]
	s_barrier
	s_cbranch_scc0 .LBB0_672
	s_lshl_b32 s10, s92, 8
	s_or_b32 s12, s10, s82
	v_add_u32_e32 v130, s12, v204
	v_ashrrev_i32_e32 v131, 31, v130
	v_lshlrev_b64 v[132:133], 2, v[130:131]
	v_lshl_add_u64 v[134:135], s[38:39], 0, v[132:133]
	v_lshl_add_u64 v[132:133], s[48:49], 0, v[132:133]
	global_load_dword v146, v[134:135], off
	global_load_dword v147, v[132:133], off
	v_readlane_b32 s22, v254, 55
	v_readlane_b32 s23, v254, 56
	s_andn2_b64 vcc, exec, s[22:23]
	v_mov_b32_e32 v148, 0
	v_cndmask_b32_e64 v132, 0, 1, s[22:23]
	v_cmp_ne_u32_e64 s[10:11], 1, v132
	s_cbranch_vccnz .LBB0_675
	v_lshl_add_u64 v[130:131], v[130:131], 2, s[50:51]
	global_load_dword v148, v[130:131], off
